# v27 plus GEMM K-loop back-edge rotation: counter and pointer stepping and exit compare moved in front of the iteration's last barrier
# speedup vs baseline: 1.0012x; 1.0012x over previous
; #define PG8_STAGE(bufoff, gbase, voff) do { _Pragma("unroll") for (int _i = 0; _i < 2; ++_i) \
;         __builtin_amdgcn_global_load_lds((const unsigned*)((const char*)(gbase) + (voff)[_i]), (LAS unsigned*)(lds + (bufoff) + ldsw + _i * 8192), 16, 0, 0); } while (0)
; #define PG8_LDA(dst, b, h) do { _Pragma("unroll") for (int m = 0; m < 4; ++m) _Pragma("unroll") for (int k = 0; k < 2; ++k) dst[m][k] = *(const LAS bf16x8*)(lds + PG8_SA(b, h) + aoff + m * 2048 + k * 1024); } while (0)
; #define PG8_LDB(dst, b, h) do { _Pragma("unroll") for (int n = 0; n < 2; ++n) _Pragma("unroll") for (int k = 0; k < 2; ++k) dst[n][k] = *(const LAS bf16x8*)(lds + PG8_SB(b, h) + boff + n * 2048 + k * 1024); } while (0)
; #define PG8_MMA(ai, bj, At, Bt) do { __builtin_amdgcn_s_setprio(1); _Pragma("unroll") for (int m = 0; m < 4; ++m) _Pragma("unroll") for (int n = 0; n < 2; ++n) _Pragma("unroll") for (int k = 0; k < 2; ++k) \
;         acc[ai][bj][m][n] = __builtin_amdgcn_mfma_f32_16x16x32_bf16(Bt[n][k], At[m][k], acc[ai][bj][m][n], 0, 0, 0); __builtin_amdgcn_s_setprio(0); } while (0)
; #define PG8_WAIT_V(n) asm volatile("s_waitcnt vmcnt(" #n ")" ::: "memory")
; #define PG8_WAIT_L(n) asm volatile("s_waitcnt lgkmcnt(" #n ")" ::: "memory")
; #define PG8_BAR __builtin_amdgcn_s_barrier()
; #define PG8_SCHED __builtin_amdgcn_sched_barrier(0)
; template <class Epi, class Sched>
; __device__ __forceinline__ void gemm_phase(LAS unsigned char* lds, const Gemm g, const Sched& S, const Epi& E, const int wid) {
;     ...
;             const bool last = (t == nt - 2);
;             const char* a1 = cA + (size_t)(t + 1) * kstep;
;             const char* a2 = last ? nA : cA + (size_t)(t + 2) * kstep; const char* b2 = last ? nB : cB + (size_t)(t + 2) * kstep;
;             const char* a3 = a2 + kstep; const char* b3 = b2 + kstep;
;             PG8_LDB(B0, 0, 0); PG8_LDB(B1, 0, 1); PG8_SCHED; PG8_LDA(At, 0, 0); PG8_STAGE(PG8_SA(1, 1), a1 + hstepA, voffA);
;             PG8_WAIT_V(8); PG8_WAIT_L(0); PG8_BAR; PG8_MMA(0, 0, At, B0); PG8_MMA(0, 1, At, B1); PG8_BAR; PG8_SCHED;
;             PG8_LDA(At, 0, 1); PG8_STAGE(PG8_SB(0, 0), b2, voffB); PG8_STAGE(PG8_SB(0, 1), b2 + hstepB, voffB); PG8_STAGE(PG8_SA(0, 0), a2, voffA);
;             PG8_WAIT_V(8); PG8_WAIT_L(0); PG8_BAR; PG8_MMA(1, 0, At, B0); PG8_MMA(1, 1, At, B1); PG8_BAR; PG8_SCHED;
.LBB0_247:
	v_add_u32_e32 v144, s76, v171
	ds_read_b128 v[128:131], v144
	ds_read_b128 v[132:135], v144 offset:1024
	ds_read_b128 v[192:195], v144 offset:2048
	ds_read_b128 v[196:199], v144 offset:3072
	v_add_u32_e32 v144, s77, v171
	ds_read_b128 v[200:203], v144
	ds_read_b128 v[204:207], v144 offset:1024
	ds_read_b128 v[208:211], v144 offset:2048
	ds_read_b128 v[212:215], v144 offset:3072
	s_add_u32 s58, s56, 0xfffc0080
	s_addc_u32 s59, s57, -1
	s_cmp_eq_u32 s86, 12
	s_cselect_b32 s61, s16, s59
	s_cselect_b32 s60, s47, s58
	s_cselect_b32 s59, s45, s85
	s_cselect_b32 s58, s53, s84
	v_lshl_add_u64 v[168:169], s[56:57], 0, v[160:161]
	s_add_i32 m0, s55, 0xc000
	ds_read_b128 v[216:219], v188
	ds_read_b128 v[220:223], v188 offset:1024
	ds_read_b128 v[224:227], v188 offset:2048
	ds_read_b128 v[228:231], v188 offset:3072
	ds_read_b128 v[232:235], v188 offset:4096
	ds_read_b128 v[236:239], v188 offset:5120
	ds_read_b128 v[240:243], v188 offset:6144
	ds_read_b128 v[244:247], v188 offset:7168
	global_load_lds_dwordx4 v[168:169], off
	s_add_i32 m0, s55, 0xe000
	v_lshl_add_u64 v[168:169], s[56:57], 0, v[162:163]
	global_load_lds_dwordx4 v[168:169], off
	s_waitcnt vmcnt(8)
	s_waitcnt lgkmcnt(0)
	s_barrier
	s_setprio 1
	v_mfma_f32_16x16x32_bf16 v[124:127], v[128:131], v[216:219], v[124:127]
	v_mfma_f32_16x16x32_bf16 v[120:123], v[192:195], v[216:219], v[120:123]
	v_mfma_f32_16x16x32_bf16 v[108:111], v[128:131], v[224:227], v[108:111]
	v_mfma_f32_16x16x32_bf16 v[104:107], v[192:195], v[224:227], v[104:107]
	v_mfma_f32_16x16x32_bf16 v[92:95], v[128:131], v[232:235], v[92:95]
	v_mfma_f32_16x16x32_bf16 v[88:91], v[192:195], v[232:235], v[88:91]
	v_mfma_f32_16x16x32_bf16 v[76:79], v[128:131], v[240:243], v[76:79]
	v_mfma_f32_16x16x32_bf16 v[72:75], v[192:195], v[240:243], v[72:75]
	v_mfma_f32_16x16x32_bf16 v[124:127], v[132:135], v[220:223], v[124:127]
	v_mfma_f32_16x16x32_bf16 v[120:123], v[196:199], v[220:223], v[120:123]
	v_mfma_f32_16x16x32_bf16 v[108:111], v[132:135], v[228:231], v[108:111]
	v_mfma_f32_16x16x32_bf16 v[104:107], v[196:199], v[228:231], v[104:107]
	v_mfma_f32_16x16x32_bf16 v[92:95], v[132:135], v[236:239], v[92:95]
	v_mfma_f32_16x16x32_bf16 v[88:91], v[196:199], v[236:239], v[88:91]
	v_mfma_f32_16x16x32_bf16 v[76:79], v[132:135], v[244:247], v[76:79]
	v_mfma_f32_16x16x32_bf16 v[72:75], v[196:199], v[244:247], v[72:75]
	v_mfma_f32_16x16x32_bf16 v[116:119], v[200:203], v[216:219], v[116:119]
	v_mfma_f32_16x16x32_bf16 v[112:115], v[208:211], v[216:219], v[112:115]
	v_mfma_f32_16x16x32_bf16 v[100:103], v[200:203], v[224:227], v[100:103]
	v_mfma_f32_16x16x32_bf16 v[96:99], v[208:211], v[224:227], v[96:99]
	v_mfma_f32_16x16x32_bf16 v[84:87], v[200:203], v[232:235], v[84:87]
	v_mfma_f32_16x16x32_bf16 v[80:83], v[208:211], v[232:235], v[80:83]
	v_mfma_f32_16x16x32_bf16 v[68:71], v[200:203], v[240:243], v[68:71]
	v_mfma_f32_16x16x32_bf16 v[64:67], v[208:211], v[240:243], v[64:67]
	v_mfma_f32_16x16x32_bf16 v[116:119], v[204:207], v[220:223], v[116:119]
	v_mfma_f32_16x16x32_bf16 v[112:115], v[212:215], v[220:223], v[112:115]
	v_mfma_f32_16x16x32_bf16 v[100:103], v[204:207], v[228:231], v[100:103]
	v_mfma_f32_16x16x32_bf16 v[96:99], v[212:215], v[228:231], v[96:99]
	v_mfma_f32_16x16x32_bf16 v[84:87], v[204:207], v[236:239], v[84:87]
	v_mfma_f32_16x16x32_bf16 v[80:83], v[212:215], v[236:239], v[80:83]
	v_mfma_f32_16x16x32_bf16 v[68:71], v[204:207], v[244:247], v[68:71]
	v_mfma_f32_16x16x32_bf16 v[64:67], v[212:215], v[244:247], v[64:67]
	s_setprio 0
	s_barrier
	s_add_i32 s87, s76, s65
	v_lshl_add_u64 v[168:169], s[58:59], 0, v[138:139]
	s_mov_b32 m0, s87
	ds_read_b128 v[216:219], v188 offset:16384
	ds_read_b128 v[220:223], v188 offset:17408
	ds_read_b128 v[224:227], v188 offset:18432
	ds_read_b128 v[228:231], v188 offset:19456
	ds_read_b128 v[232:235], v188 offset:20480
	ds_read_b128 v[236:239], v188 offset:21504
	ds_read_b128 v[240:243], v188 offset:22528
	ds_read_b128 v[244:247], v188 offset:23552
	global_load_lds_dwordx4 v[168:169], off
	s_add_i32 m0, s87, 0x2000
	s_add_u32 s88, s58, 0x40000
	v_lshl_add_u64 v[248:249], s[58:59], 0, v[142:143]
	s_addc_u32 s89, s59, 0
	s_add_i32 s87, s77, s65
	global_load_lds_dwordx4 v[248:249], off
	v_lshl_add_u64 v[250:251], s[88:89], 0, v[138:139]
	s_mov_b32 m0, s87
	v_lshl_add_u64 v[252:253], s[60:61], 0, v[140:141]
	global_load_lds_dwordx4 v[250:251], off
	s_add_i32 m0, s87, 0x2000
	v_lshl_add_u64 v[250:251], s[88:89], 0, v[142:143]
	global_load_lds_dwordx4 v[250:251], off
	s_mov_b32 m0, s55
	v_lshl_add_u64 v[250:251], s[60:61], 0, v[136:137]
	global_load_lds_dwordx4 v[250:251], off
	s_mov_b32 m0, s66
	s_nop 0
	global_load_lds_dwordx4 v[252:253], off
	s_waitcnt vmcnt(8)
	s_waitcnt lgkmcnt(0)
	s_barrier
; #define PG8_STAGE(bufoff, gbase, voff) do { _Pragma("unroll") for (int _i = 0; _i < 2; ++_i) \
;         __builtin_amdgcn_global_load_lds((const unsigned*)((const char*)(gbase) + (voff)[_i]), (LAS unsigned*)(lds + (bufoff) + ldsw + _i * 8192), 16, 0, 0); } while (0)
; #define PG8_LDA(dst, b, h) do { _Pragma("unroll") for (int m = 0; m < 4; ++m) _Pragma("unroll") for (int k = 0; k < 2; ++k) dst[m][k] = *(const LAS bf16x8*)(lds + PG8_SA(b, h) + aoff + m * 2048 + k * 1024); } while (0)
; #define PG8_LDB(dst, b, h) do { _Pragma("unroll") for (int n = 0; n < 2; ++n) _Pragma("unroll") for (int k = 0; k < 2; ++k) dst[n][k] = *(const LAS bf16x8*)(lds + PG8_SB(b, h) + boff + n * 2048 + k * 1024); } while (0)
; #define PG8_MMA(ai, bj, At, Bt) do { __builtin_amdgcn_s_setprio(1); _Pragma("unroll") for (int m = 0; m < 4; ++m) _Pragma("unroll") for (int n = 0; n < 2; ++n) _Pragma("unroll") for (int k = 0; k < 2; ++k) \
;         acc[ai][bj][m][n] = __builtin_amdgcn_mfma_f32_16x16x32_bf16(Bt[n][k], At[m][k], acc[ai][bj][m][n], 0, 0, 0); __builtin_amdgcn_s_setprio(0); } while (0)
; #define PG8_WAIT_V(n) asm volatile("s_waitcnt vmcnt(" #n ")" ::: "memory")
; #define PG8_WAIT_L(n) asm volatile("s_waitcnt lgkmcnt(" #n ")" ::: "memory")
; #define PG8_BAR __builtin_amdgcn_s_barrier()
; #define PG8_SCHED __builtin_amdgcn_sched_barrier(0)
; template <class Epi, class Sched>
; __device__ __forceinline__ void gemm_phase(LAS unsigned char* lds, const Gemm g, const Sched& S, const Epi& E, const int wid) {
;     ...
;             PG8_WAIT_V(8); PG8_WAIT_L(0); PG8_BAR; PG8_MMA(1, 0, At, B0); PG8_MMA(1, 1, At, B1); PG8_BAR; PG8_SCHED;
;             PG8_LDB(B0, 1, 0); PG8_LDB(B1, 1, 1); PG8_SCHED; PG8_LDA(At, 1, 0); PG8_STAGE(PG8_SA(0, 1), a2 + hstepA, voffA);
;             PG8_WAIT_V(8); PG8_WAIT_L(0); PG8_BAR; PG8_MMA(0, 0, At, B0); PG8_MMA(0, 1, At, B1); PG8_BAR; PG8_SCHED;
	s_setprio 1
	v_mfma_f32_16x16x32_bf16 v[60:63], v[128:131], v[216:219], v[60:63]
	v_mfma_f32_16x16x32_bf16 v[56:59], v[192:195], v[216:219], v[56:59]
	v_mfma_f32_16x16x32_bf16 v[44:47], v[128:131], v[224:227], v[44:47]
	v_mfma_f32_16x16x32_bf16 v[40:43], v[192:195], v[224:227], v[40:43]
	v_mfma_f32_16x16x32_bf16 v[28:31], v[128:131], v[232:235], v[28:31]
	v_mfma_f32_16x16x32_bf16 v[24:27], v[192:195], v[232:235], v[24:27]
	v_mfma_f32_16x16x32_bf16 v[12:15], v[128:131], v[240:243], v[12:15]
	v_mfma_f32_16x16x32_bf16 v[8:11], v[192:195], v[240:243], v[8:11]
	v_mfma_f32_16x16x32_bf16 v[60:63], v[132:135], v[220:223], v[60:63]
	v_mfma_f32_16x16x32_bf16 v[56:59], v[196:199], v[220:223], v[56:59]
	v_mfma_f32_16x16x32_bf16 v[44:47], v[132:135], v[228:231], v[44:47]
	v_mfma_f32_16x16x32_bf16 v[40:43], v[196:199], v[228:231], v[40:43]
	v_mfma_f32_16x16x32_bf16 v[28:31], v[132:135], v[236:239], v[28:31]
	v_mfma_f32_16x16x32_bf16 v[24:27], v[196:199], v[236:239], v[24:27]
	v_mfma_f32_16x16x32_bf16 v[12:15], v[132:135], v[244:247], v[12:15]
	v_mfma_f32_16x16x32_bf16 v[8:11], v[196:199], v[244:247], v[8:11]
	v_mfma_f32_16x16x32_bf16 v[52:55], v[200:203], v[216:219], v[52:55]
	v_mfma_f32_16x16x32_bf16 v[48:51], v[208:211], v[216:219], v[48:51]
	v_mfma_f32_16x16x32_bf16 v[36:39], v[200:203], v[224:227], v[36:39]
	v_mfma_f32_16x16x32_bf16 v[32:35], v[208:211], v[224:227], v[32:35]
	v_mfma_f32_16x16x32_bf16 v[20:23], v[200:203], v[232:235], v[20:23]
	v_mfma_f32_16x16x32_bf16 v[16:19], v[208:211], v[232:235], v[16:19]
	v_mfma_f32_16x16x32_bf16 v[4:7], v[200:203], v[240:243], v[4:7]
	v_mfma_f32_16x16x32_bf16 v[0:3], v[208:211], v[240:243], v[0:3]
	v_mfma_f32_16x16x32_bf16 v[52:55], v[204:207], v[220:223], v[52:55]
	v_mfma_f32_16x16x32_bf16 v[48:51], v[212:215], v[220:223], v[48:51]
	v_mfma_f32_16x16x32_bf16 v[36:39], v[204:207], v[228:231], v[36:39]
	v_mfma_f32_16x16x32_bf16 v[32:35], v[212:215], v[228:231], v[32:35]
	v_mfma_f32_16x16x32_bf16 v[20:23], v[204:207], v[236:239], v[20:23]
	v_mfma_f32_16x16x32_bf16 v[16:19], v[212:215], v[236:239], v[16:19]
	v_mfma_f32_16x16x32_bf16 v[4:7], v[204:207], v[244:247], v[4:7]
	v_mfma_f32_16x16x32_bf16 v[0:3], v[212:215], v[244:247], v[0:3]
	s_setprio 0
	s_barrier
	s_add_i32 s87, 0, 0x18000
	v_add_u32_e32 v144, s87, v171
	s_add_i32 s88, 0, 0x1c000
	ds_read_b128 v[128:131], v144
	ds_read_b128 v[132:135], v144 offset:1024
	ds_read_b128 v[192:195], v144 offset:2048
	ds_read_b128 v[196:199], v144 offset:3072
	v_add_u32_e32 v144, s88, v171
	ds_read_b128 v[200:203], v144
	ds_read_b128 v[204:207], v144 offset:1024
	ds_read_b128 v[208:211], v144 offset:2048
	ds_read_b128 v[212:215], v144 offset:3072
	s_add_u32 s60, s60, 0x40000
	s_addc_u32 s61, s61, 0
	s_mov_b32 m0, s67
	v_lshl_add_u64 v[254:255], s[60:61], 0, v[136:137]
	ds_read_b128 v[216:219], v188 offset:32768
	ds_read_b128 v[220:223], v188 offset:33792
	ds_read_b128 v[224:227], v188 offset:34816
	ds_read_b128 v[228:231], v188 offset:35840
	ds_read_b128 v[232:235], v188 offset:36864
	ds_read_b128 v[236:239], v188 offset:37888
	ds_read_b128 v[240:243], v188 offset:38912
	ds_read_b128 v[244:247], v188 offset:39936
	global_load_lds_dwordx4 v[254:255], off
	s_mov_b32 m0, s68
	v_lshl_add_u64 v[254:255], s[60:61], 0, v[140:141]
	global_load_lds_dwordx4 v[254:255], off
	s_waitcnt vmcnt(8)
	s_waitcnt lgkmcnt(0)
	s_barrier
	s_setprio 1
	v_mfma_f32_16x16x32_bf16 v[124:127], v[128:131], v[216:219], v[124:127]
	v_mfma_f32_16x16x32_bf16 v[120:123], v[192:195], v[216:219], v[120:123]
	v_mfma_f32_16x16x32_bf16 v[108:111], v[128:131], v[224:227], v[108:111]
	v_mfma_f32_16x16x32_bf16 v[104:107], v[192:195], v[224:227], v[104:107]
	v_mfma_f32_16x16x32_bf16 v[92:95], v[128:131], v[232:235], v[92:95]
	v_mfma_f32_16x16x32_bf16 v[88:91], v[192:195], v[232:235], v[88:91]
	v_mfma_f32_16x16x32_bf16 v[76:79], v[128:131], v[240:243], v[76:79]
	v_mfma_f32_16x16x32_bf16 v[72:75], v[192:195], v[240:243], v[72:75]
	v_mfma_f32_16x16x32_bf16 v[124:127], v[132:135], v[220:223], v[124:127]
	v_mfma_f32_16x16x32_bf16 v[120:123], v[196:199], v[220:223], v[120:123]
	v_mfma_f32_16x16x32_bf16 v[108:111], v[132:135], v[228:231], v[108:111]
	v_mfma_f32_16x16x32_bf16 v[104:107], v[196:199], v[228:231], v[104:107]
	v_mfma_f32_16x16x32_bf16 v[92:95], v[132:135], v[236:239], v[92:95]
	v_mfma_f32_16x16x32_bf16 v[88:91], v[196:199], v[236:239], v[88:91]
	v_mfma_f32_16x16x32_bf16 v[76:79], v[132:135], v[244:247], v[76:79]
	v_mfma_f32_16x16x32_bf16 v[72:75], v[196:199], v[244:247], v[72:75]
	v_mfma_f32_16x16x32_bf16 v[116:119], v[200:203], v[216:219], v[116:119]
	v_mfma_f32_16x16x32_bf16 v[112:115], v[208:211], v[216:219], v[112:115]
	v_mfma_f32_16x16x32_bf16 v[100:103], v[200:203], v[224:227], v[100:103]
	v_mfma_f32_16x16x32_bf16 v[96:99], v[208:211], v[224:227], v[96:99]
	v_mfma_f32_16x16x32_bf16 v[84:87], v[200:203], v[232:235], v[84:87]
	v_mfma_f32_16x16x32_bf16 v[80:83], v[208:211], v[232:235], v[80:83]
	v_mfma_f32_16x16x32_bf16 v[68:71], v[200:203], v[240:243], v[68:71]
	v_mfma_f32_16x16x32_bf16 v[64:67], v[208:211], v[240:243], v[64:67]
	v_mfma_f32_16x16x32_bf16 v[116:119], v[204:207], v[220:223], v[116:119]
	v_mfma_f32_16x16x32_bf16 v[112:115], v[212:215], v[220:223], v[112:115]
	v_mfma_f32_16x16x32_bf16 v[100:103], v[204:207], v[228:231], v[100:103]
	v_mfma_f32_16x16x32_bf16 v[96:99], v[212:215], v[228:231], v[96:99]
	v_mfma_f32_16x16x32_bf16 v[84:87], v[204:207], v[236:239], v[84:87]
	v_mfma_f32_16x16x32_bf16 v[80:83], v[212:215], v[236:239], v[80:83]
	v_mfma_f32_16x16x32_bf16 v[68:71], v[204:207], v[244:247], v[68:71]
	v_mfma_f32_16x16x32_bf16 v[64:67], v[212:215], v[244:247], v[64:67]
	s_setprio 0
	s_barrier
; #define PG8_STAGE(bufoff, gbase, voff) do { _Pragma("unroll") for (int _i = 0; _i < 2; ++_i) \
;         __builtin_amdgcn_global_load_lds((const unsigned*)((const char*)(gbase) + (voff)[_i]), (LAS unsigned*)(lds + (bufoff) + ldsw + _i * 8192), 16, 0, 0); } while (0)
; #define PG8_LDA(dst, b, h) do { _Pragma("unroll") for (int m = 0; m < 4; ++m) _Pragma("unroll") for (int k = 0; k < 2; ++k) dst[m][k] = *(const LAS bf16x8*)(lds + PG8_SA(b, h) + aoff + m * 2048 + k * 1024); } while (0)
; #define PG8_MMA(ai, bj, At, Bt) do { __builtin_amdgcn_s_setprio(1); _Pragma("unroll") for (int m = 0; m < 4; ++m) _Pragma("unroll") for (int n = 0; n < 2; ++n) _Pragma("unroll") for (int k = 0; k < 2; ++k) \
;         acc[ai][bj][m][n] = __builtin_amdgcn_mfma_f32_16x16x32_bf16(Bt[n][k], At[m][k], acc[ai][bj][m][n], 0, 0, 0); __builtin_amdgcn_s_setprio(0); } while (0)
; #define PG8_WAIT_V(n) asm volatile("s_waitcnt vmcnt(" #n ")" ::: "memory")
; #define PG8_WAIT_L(n) asm volatile("s_waitcnt lgkmcnt(" #n ")" ::: "memory")
; #define PG8_BAR __builtin_amdgcn_s_barrier()
; #define PG8_SCHED __builtin_amdgcn_sched_barrier(0)
; template <class Epi, class Sched>
; __device__ __forceinline__ void gemm_phase(LAS unsigned char* lds, const Gemm g, const Sched& S, const Epi& E, const int wid) {
;     ...
;             PG8_LDA(At, 1, 1); PG8_STAGE(PG8_SB(1, 0), b3, voffB); PG8_STAGE(PG8_SB(1, 1), b3 + hstepB, voffB); PG8_STAGE(PG8_SA(1, 0), a3, voffA);
;             PG8_WAIT_V(8); PG8_WAIT_L(0); PG8_BAR; PG8_MMA(1, 0, At, B0); PG8_MMA(1, 1, At, B1); PG8_BAR; PG8_SCHED;
;         }
;         if (wr == 0) PG8_BAR;
	s_add_i32 s60, s87, s65
	v_lshl_add_u64 v[168:169], v[168:169], 0, s[22:23]
	s_mov_b32 m0, s60
	ds_read_b128 v[216:219], v188 offset:49152
	ds_read_b128 v[220:223], v188 offset:50176
	ds_read_b128 v[224:227], v188 offset:51200
	ds_read_b128 v[228:231], v188 offset:52224
	ds_read_b128 v[232:235], v188 offset:53248
	ds_read_b128 v[236:239], v188 offset:54272
	ds_read_b128 v[240:243], v188 offset:55296
	ds_read_b128 v[244:247], v188 offset:56320
	global_load_lds_dwordx4 v[168:169], off
	s_add_i32 m0, s60, 0x2000
	s_add_u32 s58, s58, 0x40080
	v_lshl_add_u64 v[168:169], v[248:249], 0, s[22:23]
	s_addc_u32 s59, s59, 0
	s_add_i32 s60, s88, s65
	global_load_lds_dwordx4 v[168:169], off
	s_mov_b32 m0, s60
	v_lshl_add_u64 v[168:169], s[58:59], 0, v[138:139]
	global_load_lds_dwordx4 v[168:169], off
	s_add_i32 m0, s60, 0x2000
	v_lshl_add_u64 v[168:169], s[58:59], 0, v[142:143]
	global_load_lds_dwordx4 v[168:169], off
	s_mov_b32 m0, s70
	v_lshl_add_u64 v[168:169], v[250:251], 0, s[22:23]
	global_load_lds_dwordx4 v[168:169], off
	s_mov_b32 m0, s71
	v_lshl_add_u64 v[168:169], v[252:253], 0, s[22:23]
	global_load_lds_dwordx4 v[168:169], off
	s_waitcnt vmcnt(8)
	s_waitcnt lgkmcnt(0)
	s_barrier
	s_setprio 1
	v_mfma_f32_16x16x32_bf16 v[60:63], v[128:131], v[216:219], v[60:63]
	v_mfma_f32_16x16x32_bf16 v[56:59], v[192:195], v[216:219], v[56:59]
	v_mfma_f32_16x16x32_bf16 v[44:47], v[128:131], v[224:227], v[44:47]
	v_mfma_f32_16x16x32_bf16 v[40:43], v[192:195], v[224:227], v[40:43]
	v_mfma_f32_16x16x32_bf16 v[28:31], v[128:131], v[232:235], v[28:31]
	v_mfma_f32_16x16x32_bf16 v[24:27], v[192:195], v[232:235], v[24:27]
	v_mfma_f32_16x16x32_bf16 v[12:15], v[128:131], v[240:243], v[12:15]
	v_mfma_f32_16x16x32_bf16 v[8:11], v[192:195], v[240:243], v[8:11]
	v_mfma_f32_16x16x32_bf16 v[60:63], v[132:135], v[220:223], v[60:63]
	v_mfma_f32_16x16x32_bf16 v[56:59], v[196:199], v[220:223], v[56:59]
	v_mfma_f32_16x16x32_bf16 v[44:47], v[132:135], v[228:231], v[44:47]
	v_mfma_f32_16x16x32_bf16 v[40:43], v[196:199], v[228:231], v[40:43]
	v_mfma_f32_16x16x32_bf16 v[28:31], v[132:135], v[236:239], v[28:31]
	v_mfma_f32_16x16x32_bf16 v[24:27], v[196:199], v[236:239], v[24:27]
	v_mfma_f32_16x16x32_bf16 v[12:15], v[132:135], v[244:247], v[12:15]
	v_mfma_f32_16x16x32_bf16 v[8:11], v[196:199], v[244:247], v[8:11]
	v_mfma_f32_16x16x32_bf16 v[52:55], v[200:203], v[216:219], v[52:55]
	v_mfma_f32_16x16x32_bf16 v[48:51], v[208:211], v[216:219], v[48:51]
	v_mfma_f32_16x16x32_bf16 v[36:39], v[200:203], v[224:227], v[36:39]
	v_mfma_f32_16x16x32_bf16 v[32:35], v[208:211], v[224:227], v[32:35]
	v_mfma_f32_16x16x32_bf16 v[20:23], v[200:203], v[232:235], v[20:23]
	v_mfma_f32_16x16x32_bf16 v[16:19], v[208:211], v[232:235], v[16:19]
	v_mfma_f32_16x16x32_bf16 v[4:7], v[200:203], v[240:243], v[4:7]
	v_mfma_f32_16x16x32_bf16 v[0:3], v[208:211], v[240:243], v[0:3]
	v_mfma_f32_16x16x32_bf16 v[52:55], v[204:207], v[220:223], v[52:55]
	v_mfma_f32_16x16x32_bf16 v[48:51], v[212:215], v[220:223], v[48:51]
	v_mfma_f32_16x16x32_bf16 v[36:39], v[204:207], v[228:231], v[36:39]
	v_mfma_f32_16x16x32_bf16 v[32:35], v[212:215], v[228:231], v[32:35]
	v_mfma_f32_16x16x32_bf16 v[20:23], v[204:207], v[236:239], v[20:23]
	v_mfma_f32_16x16x32_bf16 v[16:19], v[212:215], v[236:239], v[16:19]
	v_mfma_f32_16x16x32_bf16 v[4:7], v[204:207], v[244:247], v[4:7]
	v_mfma_f32_16x16x32_bf16 v[0:3], v[212:215], v[244:247], v[0:3]
	s_setprio 0
	s_add_i32 s86, s86, 2
	s_add_u32 s56, s56, 0x100
	s_addc_u32 s57, s57, 0
	s_add_u32 s84, s84, 0x100
	s_addc_u32 s85, s85, 0
	s_cmp_gt_u32 s86, 13
	s_barrier
	s_cbranch_scc0 .LBB0_247
	s_and_b64 vcc, exec, s[34:35]
	s_cbranch_vccnz .LBB0_252
	s_cmp_gt_i32 s54, 4
	s_mov_b64 s[56:57], -1
	s_cbranch_scc1 .LBB0_253

; #define PG8_STAGE(bufoff, gbase, voff) do { _Pragma("unroll") for (int _i = 0; _i < 2; ++_i) \
;         __builtin_amdgcn_global_load_lds((const unsigned*)((const char*)(gbase) + (voff)[_i]), (LAS unsigned*)(lds + (bufoff) + ldsw + _i * 8192), 16, 0, 0); } while (0)
; #define PG8_LDA(dst, b, h) do { _Pragma("unroll") for (int m = 0; m < 4; ++m) _Pragma("unroll") for (int k = 0; k < 2; ++k) dst[m][k] = *(const LAS bf16x8*)(lds + PG8_SA(b, h) + aoff + m * 2048 + k * 1024); } while (0)
; #define PG8_LDB(dst, b, h) do { _Pragma("unroll") for (int n = 0; n < 2; ++n) _Pragma("unroll") for (int k = 0; k < 2; ++k) dst[n][k] = *(const LAS bf16x8*)(lds + PG8_SB(b, h) + boff + n * 2048 + k * 1024); } while (0)
; #define PG8_MMA(ai, bj, At, Bt) do { __builtin_amdgcn_s_setprio(1); _Pragma("unroll") for (int m = 0; m < 4; ++m) _Pragma("unroll") for (int n = 0; n < 2; ++n) _Pragma("unroll") for (int k = 0; k < 2; ++k) \
;         acc[ai][bj][m][n] = __builtin_amdgcn_mfma_f32_16x16x32_bf16(Bt[n][k], At[m][k], acc[ai][bj][m][n], 0, 0, 0); __builtin_amdgcn_s_setprio(0); } while (0)
; #define PG8_WAIT_V(n) asm volatile("s_waitcnt vmcnt(" #n ")" ::: "memory")
; #define PG8_WAIT_L(n) asm volatile("s_waitcnt lgkmcnt(" #n ")" ::: "memory")
; #define PG8_BAR __builtin_amdgcn_s_barrier()
; #define PG8_SCHED __builtin_amdgcn_sched_barrier(0)
; template <class Epi, class Sched>
; __device__ __forceinline__ void gemm_phase(LAS unsigned char* lds, const Gemm g, const Sched& S, const Epi& E, const int wid) {
;     ...
;             const bool last = (t == nt - 2);
;             const char* a1 = cA + (size_t)(t + 1) * kstep;
;             const char* a2 = last ? nA : cA + (size_t)(t + 2) * kstep; const char* b2 = last ? nB : cB + (size_t)(t + 2) * kstep;
;             const char* a3 = a2 + kstep; const char* b3 = b2 + kstep;
;             PG8_LDB(B0, 0, 0); PG8_LDB(B1, 0, 1); PG8_SCHED; PG8_LDA(At, 0, 0); PG8_STAGE(PG8_SA(1, 1), a1 + hstepA, voffA);
;             PG8_WAIT_V(8); PG8_WAIT_L(0); PG8_BAR; PG8_MMA(0, 0, At, B0); PG8_MMA(0, 1, At, B1); PG8_BAR; PG8_SCHED;
;             PG8_LDA(At, 0, 1); PG8_STAGE(PG8_SB(0, 0), b2, voffB); PG8_STAGE(PG8_SB(0, 1), b2 + hstepB, voffB); PG8_STAGE(PG8_SA(0, 0), a2, voffA);
;             PG8_WAIT_V(8); PG8_WAIT_L(0); PG8_BAR; PG8_MMA(1, 0, At, B0); PG8_MMA(1, 1, At, B1); PG8_BAR; PG8_SCHED;
.LBB0_459:
	ds_read_b128 v[72:75], v199
	ds_read_b128 v[80:83], v199 offset:1024
	ds_read_b128 v[84:87], v199 offset:2048
	ds_read_b128 v[92:95], v199 offset:3072
	ds_read_b128 v[144:147], v200
	ds_read_b128 v[148:151], v200 offset:1024
	ds_read_b128 v[152:155], v200 offset:2048
	ds_read_b128 v[156:159], v200 offset:3072
	s_add_u32 s56, s54, 0xfffc0080
	s_addc_u32 s57, s55, -1
	s_cmp_eq_u32 s88, 12
	s_cselect_b32 s59, s45, s57
	s_cselect_b32 s58, s51, s56
	s_cselect_b32 s57, s43, s87
	s_cselect_b32 s56, s85, s86
	v_lshl_add_u64 v[210:211], s[54:55], 0, v[164:165]
	s_add_i32 m0, s53, 0xc000
	ds_read_b128 v[172:175], v201
	ds_read_b128 v[176:179], v201 offset:1024
	ds_read_b128 v[180:183], v201 offset:2048
	ds_read_b128 v[184:187], v201 offset:3072
	ds_read_b128 v[188:191], v201 offset:4096
	ds_read_b128 v[192:195], v201 offset:5120
	ds_read_b128 v[202:205], v201 offset:6144
	ds_read_b128 v[206:209], v201 offset:7168
	global_load_lds_dwordx4 v[210:211], off
	s_add_i32 m0, s53, 0xe000
	v_lshl_add_u64 v[210:211], s[54:55], 0, v[166:167]
	global_load_lds_dwordx4 v[210:211], off
	s_waitcnt vmcnt(8)
	s_waitcnt lgkmcnt(0)
	s_barrier
	s_setprio 1
	v_mfma_f32_16x16x32_bf16 v[140:143], v[72:75], v[172:175], v[140:143]
	v_mfma_f32_16x16x32_bf16 v[136:139], v[84:87], v[172:175], v[136:139]
	v_mfma_f32_16x16x32_bf16 v[124:127], v[72:75], v[180:183], v[124:127]
	v_mfma_f32_16x16x32_bf16 v[120:123], v[84:87], v[180:183], v[120:123]
	v_mfma_f32_16x16x32_bf16 v[108:111], v[72:75], v[188:191], v[108:111]
	v_mfma_f32_16x16x32_bf16 v[104:107], v[84:87], v[188:191], v[104:107]
	v_mfma_f32_16x16x32_bf16 v[88:91], v[72:75], v[202:205], v[88:91]
	v_mfma_f32_16x16x32_bf16 v[76:79], v[84:87], v[202:205], v[76:79]
	v_mfma_f32_16x16x32_bf16 v[140:143], v[80:83], v[176:179], v[140:143]
	v_mfma_f32_16x16x32_bf16 v[136:139], v[92:95], v[176:179], v[136:139]
	v_mfma_f32_16x16x32_bf16 v[124:127], v[80:83], v[184:187], v[124:127]
	v_mfma_f32_16x16x32_bf16 v[120:123], v[92:95], v[184:187], v[120:123]
	v_mfma_f32_16x16x32_bf16 v[108:111], v[80:83], v[192:195], v[108:111]
	v_mfma_f32_16x16x32_bf16 v[104:107], v[92:95], v[192:195], v[104:107]
	v_mfma_f32_16x16x32_bf16 v[88:91], v[80:83], v[206:209], v[88:91]
	v_mfma_f32_16x16x32_bf16 v[76:79], v[92:95], v[206:209], v[76:79]
	v_mfma_f32_16x16x32_bf16 v[132:135], v[144:147], v[172:175], v[132:135]
	v_mfma_f32_16x16x32_bf16 v[128:131], v[152:155], v[172:175], v[128:131]
	v_mfma_f32_16x16x32_bf16 v[116:119], v[144:147], v[180:183], v[116:119]
	v_mfma_f32_16x16x32_bf16 v[112:115], v[152:155], v[180:183], v[112:115]
	v_mfma_f32_16x16x32_bf16 v[100:103], v[144:147], v[188:191], v[100:103]
	v_mfma_f32_16x16x32_bf16 v[96:99], v[152:155], v[188:191], v[96:99]
	v_mfma_f32_16x16x32_bf16 v[68:71], v[144:147], v[202:205], v[68:71]
	v_mfma_f32_16x16x32_bf16 v[64:67], v[152:155], v[202:205], v[64:67]
	v_mfma_f32_16x16x32_bf16 v[132:135], v[148:151], v[176:179], v[132:135]
	v_mfma_f32_16x16x32_bf16 v[128:131], v[156:159], v[176:179], v[128:131]
	v_mfma_f32_16x16x32_bf16 v[116:119], v[148:151], v[184:187], v[116:119]
	v_mfma_f32_16x16x32_bf16 v[112:115], v[156:159], v[184:187], v[112:115]
	v_mfma_f32_16x16x32_bf16 v[100:103], v[148:151], v[192:195], v[100:103]
	v_mfma_f32_16x16x32_bf16 v[96:99], v[156:159], v[192:195], v[96:99]
	v_mfma_f32_16x16x32_bf16 v[68:71], v[148:151], v[206:209], v[68:71]
	v_mfma_f32_16x16x32_bf16 v[64:67], v[156:159], v[206:209], v[64:67]
	s_setprio 0
	s_barrier
	s_add_i32 s89, s78, s63
	v_lshl_add_u64 v[210:211], s[56:57], 0, v[160:161]
	s_mov_b32 m0, s89
	ds_read_b128 v[172:175], v201 offset:16384
	ds_read_b128 v[176:179], v201 offset:17408
	ds_read_b128 v[180:183], v201 offset:18432
	ds_read_b128 v[184:187], v201 offset:19456
	ds_read_b128 v[188:191], v201 offset:20480
	ds_read_b128 v[192:195], v201 offset:21504
	ds_read_b128 v[202:205], v201 offset:22528
	ds_read_b128 v[206:209], v201 offset:23552
	global_load_lds_dwordx4 v[210:211], off
	s_add_i32 m0, s89, 0x2000
	s_add_u32 s90, s56, 0x40000
	v_lshl_add_u64 v[212:213], s[56:57], 0, v[162:163]
	s_addc_u32 s91, s57, 0
	s_add_i32 s89, s79, s63
	global_load_lds_dwordx4 v[212:213], off
	v_lshl_add_u64 v[214:215], s[90:91], 0, v[160:161]
	s_mov_b32 m0, s89
	v_lshl_add_u64 v[216:217], s[58:59], 0, v[162:163]
	global_load_lds_dwordx4 v[214:215], off
	s_add_i32 m0, s89, 0x2000
	v_lshl_add_u64 v[214:215], s[90:91], 0, v[162:163]
	global_load_lds_dwordx4 v[214:215], off
	s_mov_b32 m0, s53
	v_lshl_add_u64 v[214:215], s[58:59], 0, v[160:161]
	global_load_lds_dwordx4 v[214:215], off
	s_mov_b32 m0, s64
	s_nop 0
	global_load_lds_dwordx4 v[216:217], off
	s_waitcnt vmcnt(8)
	s_waitcnt lgkmcnt(0)
	s_barrier
; #define PG8_STAGE(bufoff, gbase, voff) do { _Pragma("unroll") for (int _i = 0; _i < 2; ++_i) \
;         __builtin_amdgcn_global_load_lds((const unsigned*)((const char*)(gbase) + (voff)[_i]), (LAS unsigned*)(lds + (bufoff) + ldsw + _i * 8192), 16, 0, 0); } while (0)
; #define PG8_LDA(dst, b, h) do { _Pragma("unroll") for (int m = 0; m < 4; ++m) _Pragma("unroll") for (int k = 0; k < 2; ++k) dst[m][k] = *(const LAS bf16x8*)(lds + PG8_SA(b, h) + aoff + m * 2048 + k * 1024); } while (0)
; #define PG8_LDB(dst, b, h) do { _Pragma("unroll") for (int n = 0; n < 2; ++n) _Pragma("unroll") for (int k = 0; k < 2; ++k) dst[n][k] = *(const LAS bf16x8*)(lds + PG8_SB(b, h) + boff + n * 2048 + k * 1024); } while (0)
; #define PG8_MMA(ai, bj, At, Bt) do { __builtin_amdgcn_s_setprio(1); _Pragma("unroll") for (int m = 0; m < 4; ++m) _Pragma("unroll") for (int n = 0; n < 2; ++n) _Pragma("unroll") for (int k = 0; k < 2; ++k) \
;         acc[ai][bj][m][n] = __builtin_amdgcn_mfma_f32_16x16x32_bf16(Bt[n][k], At[m][k], acc[ai][bj][m][n], 0, 0, 0); __builtin_amdgcn_s_setprio(0); } while (0)
; #define PG8_WAIT_V(n) asm volatile("s_waitcnt vmcnt(" #n ")" ::: "memory")
; #define PG8_WAIT_L(n) asm volatile("s_waitcnt lgkmcnt(" #n ")" ::: "memory")
; #define PG8_BAR __builtin_amdgcn_s_barrier()
; #define PG8_SCHED __builtin_amdgcn_sched_barrier(0)
; template <class Epi, class Sched>
; __device__ __forceinline__ void gemm_phase(LAS unsigned char* lds, const Gemm g, const Sched& S, const Epi& E, const int wid) {
;     ...
;             PG8_WAIT_V(8); PG8_WAIT_L(0); PG8_BAR; PG8_MMA(1, 0, At, B0); PG8_MMA(1, 1, At, B1); PG8_BAR; PG8_SCHED;
;             PG8_LDB(B0, 1, 0); PG8_LDB(B1, 1, 1); PG8_SCHED; PG8_LDA(At, 1, 0); PG8_STAGE(PG8_SA(0, 1), a2 + hstepA, voffA);
;             PG8_WAIT_V(8); PG8_WAIT_L(0); PG8_BAR; PG8_MMA(0, 0, At, B0); PG8_MMA(0, 1, At, B1); PG8_BAR; PG8_SCHED;
	s_setprio 1
	v_mfma_f32_16x16x32_bf16 v[60:63], v[72:75], v[172:175], v[60:63]
	v_mfma_f32_16x16x32_bf16 v[56:59], v[84:87], v[172:175], v[56:59]
	v_mfma_f32_16x16x32_bf16 v[44:47], v[72:75], v[180:183], v[44:47]
	v_mfma_f32_16x16x32_bf16 v[40:43], v[84:87], v[180:183], v[40:43]
	v_mfma_f32_16x16x32_bf16 v[28:31], v[72:75], v[188:191], v[28:31]
	v_mfma_f32_16x16x32_bf16 v[24:27], v[84:87], v[188:191], v[24:27]
	v_mfma_f32_16x16x32_bf16 v[12:15], v[72:75], v[202:205], v[12:15]
	v_mfma_f32_16x16x32_bf16 v[8:11], v[84:87], v[202:205], v[8:11]
	v_mfma_f32_16x16x32_bf16 v[60:63], v[80:83], v[176:179], v[60:63]
	v_mfma_f32_16x16x32_bf16 v[56:59], v[92:95], v[176:179], v[56:59]
	v_mfma_f32_16x16x32_bf16 v[44:47], v[80:83], v[184:187], v[44:47]
	v_mfma_f32_16x16x32_bf16 v[40:43], v[92:95], v[184:187], v[40:43]
	v_mfma_f32_16x16x32_bf16 v[28:31], v[80:83], v[192:195], v[28:31]
	v_mfma_f32_16x16x32_bf16 v[24:27], v[92:95], v[192:195], v[24:27]
	v_mfma_f32_16x16x32_bf16 v[12:15], v[80:83], v[206:209], v[12:15]
	v_mfma_f32_16x16x32_bf16 v[8:11], v[92:95], v[206:209], v[8:11]
	v_mfma_f32_16x16x32_bf16 v[52:55], v[144:147], v[172:175], v[52:55]
	v_mfma_f32_16x16x32_bf16 v[48:51], v[152:155], v[172:175], v[48:51]
	v_mfma_f32_16x16x32_bf16 v[36:39], v[144:147], v[180:183], v[36:39]
	v_mfma_f32_16x16x32_bf16 v[32:35], v[152:155], v[180:183], v[32:35]
	v_mfma_f32_16x16x32_bf16 v[20:23], v[144:147], v[188:191], v[20:23]
	v_mfma_f32_16x16x32_bf16 v[16:19], v[152:155], v[188:191], v[16:19]
	v_mfma_f32_16x16x32_bf16 v[4:7], v[144:147], v[202:205], v[4:7]
	v_mfma_f32_16x16x32_bf16 v[0:3], v[152:155], v[202:205], v[0:3]
	v_mfma_f32_16x16x32_bf16 v[52:55], v[148:151], v[176:179], v[52:55]
	v_mfma_f32_16x16x32_bf16 v[48:51], v[156:159], v[176:179], v[48:51]
	v_mfma_f32_16x16x32_bf16 v[36:39], v[148:151], v[184:187], v[36:39]
	v_mfma_f32_16x16x32_bf16 v[32:35], v[156:159], v[184:187], v[32:35]
	v_mfma_f32_16x16x32_bf16 v[20:23], v[148:151], v[192:195], v[20:23]
	v_mfma_f32_16x16x32_bf16 v[16:19], v[156:159], v[192:195], v[16:19]
	v_mfma_f32_16x16x32_bf16 v[4:7], v[148:151], v[206:209], v[4:7]
	v_mfma_f32_16x16x32_bf16 v[0:3], v[156:159], v[206:209], v[0:3]
	s_setprio 0
	s_barrier
	s_add_i32 s89, 0, 0x18000
	s_add_i32 s90, 0, 0x1c000
	v_add_u32_e32 v92, s89, v197
	v_add_u32_e32 v156, s90, v197
	ds_read_b128 v[72:75], v92
	ds_read_b128 v[80:83], v92 offset:1024
	ds_read_b128 v[84:87], v92 offset:2048
	ds_read_b128 v[92:95], v92 offset:3072
	ds_read_b128 v[144:147], v156
	ds_read_b128 v[148:151], v156 offset:1024
	ds_read_b128 v[152:155], v156 offset:2048
	ds_read_b128 v[156:159], v156 offset:3072
	s_add_u32 s58, s58, 0x40000
	s_addc_u32 s59, s59, 0
	s_mov_b32 m0, s65
	v_lshl_add_u64 v[218:219], s[58:59], 0, v[160:161]
	ds_read_b128 v[172:175], v201 offset:32768
	ds_read_b128 v[176:179], v201 offset:33792
	ds_read_b128 v[180:183], v201 offset:34816
	ds_read_b128 v[184:187], v201 offset:35840
	ds_read_b128 v[188:191], v201 offset:36864
	ds_read_b128 v[192:195], v201 offset:37888
	ds_read_b128 v[202:205], v201 offset:38912
	ds_read_b128 v[206:209], v201 offset:39936
	global_load_lds_dwordx4 v[218:219], off
	s_mov_b32 m0, s66
	v_lshl_add_u64 v[218:219], s[58:59], 0, v[162:163]
	global_load_lds_dwordx4 v[218:219], off
	s_waitcnt vmcnt(8)
	s_waitcnt lgkmcnt(0)
	s_barrier
	s_setprio 1
	v_mfma_f32_16x16x32_bf16 v[140:143], v[72:75], v[172:175], v[140:143]
	v_mfma_f32_16x16x32_bf16 v[136:139], v[84:87], v[172:175], v[136:139]
	v_mfma_f32_16x16x32_bf16 v[124:127], v[72:75], v[180:183], v[124:127]
	v_mfma_f32_16x16x32_bf16 v[120:123], v[84:87], v[180:183], v[120:123]
	v_mfma_f32_16x16x32_bf16 v[108:111], v[72:75], v[188:191], v[108:111]
	v_mfma_f32_16x16x32_bf16 v[104:107], v[84:87], v[188:191], v[104:107]
	v_mfma_f32_16x16x32_bf16 v[88:91], v[72:75], v[202:205], v[88:91]
	v_mfma_f32_16x16x32_bf16 v[76:79], v[84:87], v[202:205], v[76:79]
	v_mfma_f32_16x16x32_bf16 v[140:143], v[80:83], v[176:179], v[140:143]
	v_mfma_f32_16x16x32_bf16 v[136:139], v[92:95], v[176:179], v[136:139]
	v_mfma_f32_16x16x32_bf16 v[124:127], v[80:83], v[184:187], v[124:127]
	v_mfma_f32_16x16x32_bf16 v[120:123], v[92:95], v[184:187], v[120:123]
	v_mfma_f32_16x16x32_bf16 v[108:111], v[80:83], v[192:195], v[108:111]
	v_mfma_f32_16x16x32_bf16 v[104:107], v[92:95], v[192:195], v[104:107]
	v_mfma_f32_16x16x32_bf16 v[88:91], v[80:83], v[206:209], v[88:91]
	v_mfma_f32_16x16x32_bf16 v[76:79], v[92:95], v[206:209], v[76:79]
	v_mfma_f32_16x16x32_bf16 v[132:135], v[144:147], v[172:175], v[132:135]
	v_mfma_f32_16x16x32_bf16 v[128:131], v[152:155], v[172:175], v[128:131]
	v_mfma_f32_16x16x32_bf16 v[116:119], v[144:147], v[180:183], v[116:119]
	v_mfma_f32_16x16x32_bf16 v[112:115], v[152:155], v[180:183], v[112:115]
	v_mfma_f32_16x16x32_bf16 v[100:103], v[144:147], v[188:191], v[100:103]
	v_mfma_f32_16x16x32_bf16 v[96:99], v[152:155], v[188:191], v[96:99]
	v_mfma_f32_16x16x32_bf16 v[68:71], v[144:147], v[202:205], v[68:71]
	v_mfma_f32_16x16x32_bf16 v[64:67], v[152:155], v[202:205], v[64:67]
	v_mfma_f32_16x16x32_bf16 v[132:135], v[148:151], v[176:179], v[132:135]
	v_mfma_f32_16x16x32_bf16 v[128:131], v[156:159], v[176:179], v[128:131]
	v_mfma_f32_16x16x32_bf16 v[116:119], v[148:151], v[184:187], v[116:119]
	v_mfma_f32_16x16x32_bf16 v[112:115], v[156:159], v[184:187], v[112:115]
	v_mfma_f32_16x16x32_bf16 v[100:103], v[148:151], v[192:195], v[100:103]
	v_mfma_f32_16x16x32_bf16 v[96:99], v[156:159], v[192:195], v[96:99]
	v_mfma_f32_16x16x32_bf16 v[68:71], v[148:151], v[206:209], v[68:71]
	v_mfma_f32_16x16x32_bf16 v[64:67], v[156:159], v[206:209], v[64:67]
	s_setprio 0
	s_barrier
; #define PG8_STAGE(bufoff, gbase, voff) do { _Pragma("unroll") for (int _i = 0; _i < 2; ++_i) \
;         __builtin_amdgcn_global_load_lds((const unsigned*)((const char*)(gbase) + (voff)[_i]), (LAS unsigned*)(lds + (bufoff) + ldsw + _i * 8192), 16, 0, 0); } while (0)
; #define PG8_LDA(dst, b, h) do { _Pragma("unroll") for (int m = 0; m < 4; ++m) _Pragma("unroll") for (int k = 0; k < 2; ++k) dst[m][k] = *(const LAS bf16x8*)(lds + PG8_SA(b, h) + aoff + m * 2048 + k * 1024); } while (0)
; #define PG8_MMA(ai, bj, At, Bt) do { __builtin_amdgcn_s_setprio(1); _Pragma("unroll") for (int m = 0; m < 4; ++m) _Pragma("unroll") for (int n = 0; n < 2; ++n) _Pragma("unroll") for (int k = 0; k < 2; ++k) \
;         acc[ai][bj][m][n] = __builtin_amdgcn_mfma_f32_16x16x32_bf16(Bt[n][k], At[m][k], acc[ai][bj][m][n], 0, 0, 0); __builtin_amdgcn_s_setprio(0); } while (0)
; #define PG8_WAIT_V(n) asm volatile("s_waitcnt vmcnt(" #n ")" ::: "memory")
; #define PG8_WAIT_L(n) asm volatile("s_waitcnt lgkmcnt(" #n ")" ::: "memory")
; #define PG8_BAR __builtin_amdgcn_s_barrier()
; #define PG8_SCHED __builtin_amdgcn_sched_barrier(0)
; template <class Epi, class Sched>
; __device__ __forceinline__ void gemm_phase(LAS unsigned char* lds, const Gemm g, const Sched& S, const Epi& E, const int wid) {
;     ...
;             PG8_LDA(At, 1, 1); PG8_STAGE(PG8_SB(1, 0), b3, voffB); PG8_STAGE(PG8_SB(1, 1), b3 + hstepB, voffB); PG8_STAGE(PG8_SA(1, 0), a3, voffA);
;             PG8_WAIT_V(8); PG8_WAIT_L(0); PG8_BAR; PG8_MMA(1, 0, At, B0); PG8_MMA(1, 1, At, B1); PG8_BAR; PG8_SCHED;
;         }
;         if (wr == 0) PG8_BAR;
	s_add_i32 s58, s89, s63
	v_lshl_add_u64 v[210:211], v[210:211], 0, s[34:35]
	s_mov_b32 m0, s58
	ds_read_b128 v[172:175], v201 offset:49152
	ds_read_b128 v[176:179], v201 offset:50176
	ds_read_b128 v[180:183], v201 offset:51200
	ds_read_b128 v[184:187], v201 offset:52224
	ds_read_b128 v[188:191], v201 offset:53248
	ds_read_b128 v[192:195], v201 offset:54272
	ds_read_b128 v[202:205], v201 offset:55296
	ds_read_b128 v[206:209], v201 offset:56320
	global_load_lds_dwordx4 v[210:211], off
	s_add_i32 m0, s58, 0x2000
	s_add_u32 s56, s56, 0x40080
	v_lshl_add_u64 v[210:211], v[212:213], 0, s[34:35]
	s_addc_u32 s57, s57, 0
	s_add_i32 s58, s90, s63
	global_load_lds_dwordx4 v[210:211], off
	s_mov_b32 m0, s58
	v_lshl_add_u64 v[210:211], s[56:57], 0, v[160:161]
	global_load_lds_dwordx4 v[210:211], off
	s_add_i32 m0, s58, 0x2000
	v_lshl_add_u64 v[210:211], s[56:57], 0, v[162:163]
	global_load_lds_dwordx4 v[210:211], off
	s_mov_b32 m0, s72
	v_lshl_add_u64 v[210:211], v[214:215], 0, s[34:35]
	global_load_lds_dwordx4 v[210:211], off
	s_mov_b32 m0, s73
	v_lshl_add_u64 v[210:211], v[216:217], 0, s[34:35]
	global_load_lds_dwordx4 v[210:211], off
	s_waitcnt vmcnt(8)
	s_waitcnt lgkmcnt(0)
	s_barrier
	s_setprio 1
	v_mfma_f32_16x16x32_bf16 v[60:63], v[72:75], v[172:175], v[60:63]
	v_mfma_f32_16x16x32_bf16 v[56:59], v[84:87], v[172:175], v[56:59]
	v_mfma_f32_16x16x32_bf16 v[44:47], v[72:75], v[180:183], v[44:47]
	v_mfma_f32_16x16x32_bf16 v[40:43], v[84:87], v[180:183], v[40:43]
	v_mfma_f32_16x16x32_bf16 v[28:31], v[72:75], v[188:191], v[28:31]
	v_mfma_f32_16x16x32_bf16 v[24:27], v[84:87], v[188:191], v[24:27]
	v_mfma_f32_16x16x32_bf16 v[12:15], v[72:75], v[202:205], v[12:15]
	v_mfma_f32_16x16x32_bf16 v[8:11], v[84:87], v[202:205], v[8:11]
	v_mfma_f32_16x16x32_bf16 v[60:63], v[80:83], v[176:179], v[60:63]
	v_mfma_f32_16x16x32_bf16 v[56:59], v[92:95], v[176:179], v[56:59]
	v_mfma_f32_16x16x32_bf16 v[44:47], v[80:83], v[184:187], v[44:47]
	v_mfma_f32_16x16x32_bf16 v[40:43], v[92:95], v[184:187], v[40:43]
	v_mfma_f32_16x16x32_bf16 v[28:31], v[80:83], v[192:195], v[28:31]
	v_mfma_f32_16x16x32_bf16 v[24:27], v[92:95], v[192:195], v[24:27]
	v_mfma_f32_16x16x32_bf16 v[12:15], v[80:83], v[206:209], v[12:15]
	v_mfma_f32_16x16x32_bf16 v[8:11], v[92:95], v[206:209], v[8:11]
	v_mfma_f32_16x16x32_bf16 v[52:55], v[144:147], v[172:175], v[52:55]
	v_mfma_f32_16x16x32_bf16 v[48:51], v[152:155], v[172:175], v[48:51]
	v_mfma_f32_16x16x32_bf16 v[36:39], v[144:147], v[180:183], v[36:39]
	v_mfma_f32_16x16x32_bf16 v[32:35], v[152:155], v[180:183], v[32:35]
	v_mfma_f32_16x16x32_bf16 v[20:23], v[144:147], v[188:191], v[20:23]
	v_mfma_f32_16x16x32_bf16 v[16:19], v[152:155], v[188:191], v[16:19]
	v_mfma_f32_16x16x32_bf16 v[4:7], v[144:147], v[202:205], v[4:7]
	v_mfma_f32_16x16x32_bf16 v[0:3], v[152:155], v[202:205], v[0:3]
	v_mfma_f32_16x16x32_bf16 v[52:55], v[148:151], v[176:179], v[52:55]
	v_mfma_f32_16x16x32_bf16 v[48:51], v[156:159], v[176:179], v[48:51]
	v_mfma_f32_16x16x32_bf16 v[36:39], v[148:151], v[184:187], v[36:39]
	v_mfma_f32_16x16x32_bf16 v[32:35], v[156:159], v[184:187], v[32:35]
	v_mfma_f32_16x16x32_bf16 v[20:23], v[148:151], v[192:195], v[20:23]
	v_mfma_f32_16x16x32_bf16 v[16:19], v[156:159], v[192:195], v[16:19]
	v_mfma_f32_16x16x32_bf16 v[4:7], v[148:151], v[206:209], v[4:7]
	v_mfma_f32_16x16x32_bf16 v[0:3], v[156:159], v[206:209], v[0:3]
	s_setprio 0
	s_add_i32 s88, s88, 2
	s_add_u32 s54, s54, 0x100
	s_addc_u32 s55, s55, 0
	s_add_u32 s86, s86, 0x100
	s_addc_u32 s87, s87, 0
	s_cmp_gt_u32 s88, 13
	s_barrier
	s_cbranch_scc0 .LBB0_459
	s_and_b64 vcc, exec, s[38:39]
	s_cbranch_vccz .LBB0_462
	s_barrier

; #define PG8_STAGE(bufoff, gbase, voff) do { _Pragma("unroll") for (int _i = 0; _i < 2; ++_i) \
;         __builtin_amdgcn_global_load_lds((const unsigned*)((const char*)(gbase) + (voff)[_i]), (LAS unsigned*)(lds + (bufoff) + ldsw + _i * 8192), 16, 0, 0); } while (0)
; #define PG8_LDA(dst, b, h) do { _Pragma("unroll") for (int m = 0; m < 4; ++m) _Pragma("unroll") for (int k = 0; k < 2; ++k) dst[m][k] = *(const LAS bf16x8*)(lds + PG8_SA(b, h) + aoff + m * 2048 + k * 1024); } while (0)
; #define PG8_LDB(dst, b, h) do { _Pragma("unroll") for (int n = 0; n < 2; ++n) _Pragma("unroll") for (int k = 0; k < 2; ++k) dst[n][k] = *(const LAS bf16x8*)(lds + PG8_SB(b, h) + boff + n * 2048 + k * 1024); } while (0)
; #define PG8_MMA(ai, bj, At, Bt) do { __builtin_amdgcn_s_setprio(1); _Pragma("unroll") for (int m = 0; m < 4; ++m) _Pragma("unroll") for (int n = 0; n < 2; ++n) _Pragma("unroll") for (int k = 0; k < 2; ++k) \
;         acc[ai][bj][m][n] = __builtin_amdgcn_mfma_f32_16x16x32_bf16(Bt[n][k], At[m][k], acc[ai][bj][m][n], 0, 0, 0); __builtin_amdgcn_s_setprio(0); } while (0)
; #define PG8_WAIT_V(n) asm volatile("s_waitcnt vmcnt(" #n ")" ::: "memory")
; #define PG8_WAIT_L(n) asm volatile("s_waitcnt lgkmcnt(" #n ")" ::: "memory")
; #define PG8_BAR __builtin_amdgcn_s_barrier()
; #define PG8_SCHED __builtin_amdgcn_sched_barrier(0)
; template <class Epi, class Sched>
; __device__ __forceinline__ void gemm_phase(LAS unsigned char* lds, const Gemm g, const Sched& S, const Epi& E, const int wid) {
;     ...
;             const bool last = (t == nt - 2);
;             const char* a1 = cA + (size_t)(t + 1) * kstep;
;             const char* a2 = last ? nA : cA + (size_t)(t + 2) * kstep; const char* b2 = last ? nB : cB + (size_t)(t + 2) * kstep;
;             const char* a3 = a2 + kstep; const char* b3 = b2 + kstep;
;             PG8_LDB(B0, 0, 0); PG8_LDB(B1, 0, 1); PG8_SCHED; PG8_LDA(At, 0, 0); PG8_STAGE(PG8_SA(1, 1), a1 + hstepA, voffA);
;             PG8_WAIT_V(8); PG8_WAIT_L(0); PG8_BAR; PG8_MMA(0, 0, At, B0); PG8_MMA(0, 1, At, B1); PG8_BAR; PG8_SCHED;
;             PG8_LDA(At, 0, 1); PG8_STAGE(PG8_SB(0, 0), b2, voffB); PG8_STAGE(PG8_SB(0, 1), b2 + hstepB, voffB); PG8_STAGE(PG8_SA(0, 0), a2, voffA);
;             PG8_WAIT_V(8); PG8_WAIT_L(0); PG8_BAR; PG8_MMA(1, 0, At, B0); PG8_MMA(1, 1, At, B1); PG8_BAR; PG8_SCHED;
.LBB0_546:
	ds_read_b128 v[128:131], v167
	ds_read_b128 v[132:135], v167 offset:1024
	ds_read_b128 v[136:139], v167 offset:2048
	ds_read_b128 v[140:143], v167 offset:3072
	ds_read_b128 v[172:175], v168
	ds_read_b128 v[176:179], v168 offset:1024
	ds_read_b128 v[180:183], v168 offset:2048
	ds_read_b128 v[184:187], v168 offset:3072
	s_add_u32 s48, s46, 0xfffc0080
	s_addc_u32 s49, s47, -1
	s_cmp_eq_u32 s81, 12
	s_cselect_b32 s51, s39, s49
	s_cselect_b32 s50, s77, s48
	s_cselect_b32 s49, s37, s80
	s_cselect_b32 s48, s78, s79
	v_lshl_add_u64 v[164:165], s[46:47], 0, v[156:157]
	s_add_i32 m0, s57, 0xc000
	ds_read_b128 v[188:191], v169
	ds_read_b128 v[192:195], v169 offset:1024
	ds_read_b128 v[196:199], v169 offset:2048
	ds_read_b128 v[200:203], v169 offset:3072
	ds_read_b128 v[204:207], v169 offset:4096
	ds_read_b128 v[208:211], v169 offset:5120
	ds_read_b128 v[212:215], v169 offset:6144
	ds_read_b128 v[216:219], v169 offset:7168
	global_load_lds_dwordx4 v[164:165], off
	s_add_i32 m0, s57, 0xe000
	v_lshl_add_u64 v[164:165], s[46:47], 0, v[158:159]
	global_load_lds_dwordx4 v[164:165], off
	s_waitcnt vmcnt(8)
	s_waitcnt lgkmcnt(0)
	s_barrier
	s_setprio 1
	v_mfma_f32_16x16x32_bf16 v[124:127], v[128:131], v[188:191], v[124:127]
	v_mfma_f32_16x16x32_bf16 v[120:123], v[136:139], v[188:191], v[120:123]
	v_mfma_f32_16x16x32_bf16 v[116:119], v[128:131], v[196:199], v[116:119]
	v_mfma_f32_16x16x32_bf16 v[112:115], v[136:139], v[196:199], v[112:115]
	v_mfma_f32_16x16x32_bf16 v[108:111], v[128:131], v[204:207], v[108:111]
	v_mfma_f32_16x16x32_bf16 v[96:99], v[136:139], v[204:207], v[96:99]
	v_mfma_f32_16x16x32_bf16 v[80:83], v[128:131], v[212:215], v[80:83]
	v_mfma_f32_16x16x32_bf16 v[72:75], v[136:139], v[212:215], v[72:75]
	v_mfma_f32_16x16x32_bf16 v[124:127], v[132:135], v[192:195], v[124:127]
	v_mfma_f32_16x16x32_bf16 v[120:123], v[140:143], v[192:195], v[120:123]
	v_mfma_f32_16x16x32_bf16 v[116:119], v[132:135], v[200:203], v[116:119]
	v_mfma_f32_16x16x32_bf16 v[112:115], v[140:143], v[200:203], v[112:115]
	v_mfma_f32_16x16x32_bf16 v[108:111], v[132:135], v[208:211], v[108:111]
	v_mfma_f32_16x16x32_bf16 v[96:99], v[140:143], v[208:211], v[96:99]
	v_mfma_f32_16x16x32_bf16 v[80:83], v[132:135], v[216:219], v[80:83]
	v_mfma_f32_16x16x32_bf16 v[72:75], v[140:143], v[216:219], v[72:75]
	v_mfma_f32_16x16x32_bf16 v[104:107], v[172:175], v[188:191], v[104:107]
	v_mfma_f32_16x16x32_bf16 v[100:103], v[180:183], v[188:191], v[100:103]
	v_mfma_f32_16x16x32_bf16 v[92:95], v[172:175], v[196:199], v[92:95]
	v_mfma_f32_16x16x32_bf16 v[88:91], v[180:183], v[196:199], v[88:91]
	v_mfma_f32_16x16x32_bf16 v[84:87], v[172:175], v[204:207], v[84:87]
	v_mfma_f32_16x16x32_bf16 v[76:79], v[180:183], v[204:207], v[76:79]
	v_mfma_f32_16x16x32_bf16 v[68:71], v[172:175], v[212:215], v[68:71]
	v_mfma_f32_16x16x32_bf16 v[64:67], v[180:183], v[212:215], v[64:67]
	v_mfma_f32_16x16x32_bf16 v[104:107], v[176:179], v[192:195], v[104:107]
	v_mfma_f32_16x16x32_bf16 v[100:103], v[184:187], v[192:195], v[100:103]
	v_mfma_f32_16x16x32_bf16 v[92:95], v[176:179], v[200:203], v[92:95]
	v_mfma_f32_16x16x32_bf16 v[88:91], v[184:187], v[200:203], v[88:91]
	v_mfma_f32_16x16x32_bf16 v[84:87], v[176:179], v[208:211], v[84:87]
	v_mfma_f32_16x16x32_bf16 v[76:79], v[184:187], v[208:211], v[76:79]
	v_mfma_f32_16x16x32_bf16 v[68:71], v[176:179], v[216:219], v[68:71]
	v_mfma_f32_16x16x32_bf16 v[64:67], v[184:187], v[216:219], v[64:67]
	s_setprio 0
	s_barrier
	s_add_i32 s82, s70, s54
	v_lshl_add_u64 v[164:165], s[48:49], 0, v[148:149]
	s_mov_b32 m0, s82
	ds_read_b128 v[188:191], v169 offset:16384
	ds_read_b128 v[192:195], v169 offset:17408
	ds_read_b128 v[196:199], v169 offset:18432
	ds_read_b128 v[200:203], v169 offset:19456
	ds_read_b128 v[204:207], v169 offset:20480
	ds_read_b128 v[208:211], v169 offset:21504
	ds_read_b128 v[212:215], v169 offset:22528
	ds_read_b128 v[216:219], v169 offset:23552
	global_load_lds_dwordx4 v[164:165], off
	s_add_i32 m0, s82, 0x2000
	s_add_u32 s82, s48, 0x40000
	v_lshl_add_u64 v[220:221], s[48:49], 0, v[144:145]
	s_addc_u32 s83, s49, 0
	s_add_i32 s84, s71, s54
	global_load_lds_dwordx4 v[220:221], off
	v_lshl_add_u64 v[222:223], s[82:83], 0, v[148:149]
	s_mov_b32 m0, s84
	v_lshl_add_u64 v[224:225], s[50:51], 0, v[146:147]
	global_load_lds_dwordx4 v[222:223], off
	s_add_i32 m0, s84, 0x2000
	v_lshl_add_u64 v[222:223], s[82:83], 0, v[144:145]
	global_load_lds_dwordx4 v[222:223], off
	s_mov_b32 m0, s57
	v_lshl_add_u64 v[222:223], s[50:51], 0, v[150:151]
	global_load_lds_dwordx4 v[222:223], off
	s_mov_b32 m0, s58
	s_nop 0
	global_load_lds_dwordx4 v[224:225], off
	s_waitcnt vmcnt(8)
	s_waitcnt lgkmcnt(0)
	s_barrier
; #define PG8_STAGE(bufoff, gbase, voff) do { _Pragma("unroll") for (int _i = 0; _i < 2; ++_i) \
;         __builtin_amdgcn_global_load_lds((const unsigned*)((const char*)(gbase) + (voff)[_i]), (LAS unsigned*)(lds + (bufoff) + ldsw + _i * 8192), 16, 0, 0); } while (0)
; #define PG8_LDA(dst, b, h) do { _Pragma("unroll") for (int m = 0; m < 4; ++m) _Pragma("unroll") for (int k = 0; k < 2; ++k) dst[m][k] = *(const LAS bf16x8*)(lds + PG8_SA(b, h) + aoff + m * 2048 + k * 1024); } while (0)
; #define PG8_LDB(dst, b, h) do { _Pragma("unroll") for (int n = 0; n < 2; ++n) _Pragma("unroll") for (int k = 0; k < 2; ++k) dst[n][k] = *(const LAS bf16x8*)(lds + PG8_SB(b, h) + boff + n * 2048 + k * 1024); } while (0)
; #define PG8_MMA(ai, bj, At, Bt) do { __builtin_amdgcn_s_setprio(1); _Pragma("unroll") for (int m = 0; m < 4; ++m) _Pragma("unroll") for (int n = 0; n < 2; ++n) _Pragma("unroll") for (int k = 0; k < 2; ++k) \
;         acc[ai][bj][m][n] = __builtin_amdgcn_mfma_f32_16x16x32_bf16(Bt[n][k], At[m][k], acc[ai][bj][m][n], 0, 0, 0); __builtin_amdgcn_s_setprio(0); } while (0)
; #define PG8_WAIT_V(n) asm volatile("s_waitcnt vmcnt(" #n ")" ::: "memory")
; #define PG8_WAIT_L(n) asm volatile("s_waitcnt lgkmcnt(" #n ")" ::: "memory")
; #define PG8_BAR __builtin_amdgcn_s_barrier()
; #define PG8_SCHED __builtin_amdgcn_sched_barrier(0)
; template <class Epi, class Sched>
; __device__ __forceinline__ void gemm_phase(LAS unsigned char* lds, const Gemm g, const Sched& S, const Epi& E, const int wid) {
;     ...
;             PG8_WAIT_V(8); PG8_WAIT_L(0); PG8_BAR; PG8_MMA(1, 0, At, B0); PG8_MMA(1, 1, At, B1); PG8_BAR; PG8_SCHED;
;             PG8_LDB(B0, 1, 0); PG8_LDB(B1, 1, 1); PG8_SCHED; PG8_LDA(At, 1, 0); PG8_STAGE(PG8_SA(0, 1), a2 + hstepA, voffA);
;             PG8_WAIT_V(8); PG8_WAIT_L(0); PG8_BAR; PG8_MMA(0, 0, At, B0); PG8_MMA(0, 1, At, B1); PG8_BAR; PG8_SCHED;
	s_setprio 1
	v_mfma_f32_16x16x32_bf16 v[60:63], v[128:131], v[188:191], v[60:63]
	v_mfma_f32_16x16x32_bf16 v[56:59], v[136:139], v[188:191], v[56:59]
	v_mfma_f32_16x16x32_bf16 v[48:51], v[128:131], v[196:199], v[48:51]
	v_mfma_f32_16x16x32_bf16 v[40:43], v[136:139], v[196:199], v[40:43]
	v_mfma_f32_16x16x32_bf16 v[32:35], v[128:131], v[204:207], v[32:35]
	v_mfma_f32_16x16x32_bf16 v[24:27], v[136:139], v[204:207], v[24:27]
	v_mfma_f32_16x16x32_bf16 v[16:19], v[128:131], v[212:215], v[16:19]
	v_mfma_f32_16x16x32_bf16 v[8:11], v[136:139], v[212:215], v[8:11]
	v_mfma_f32_16x16x32_bf16 v[60:63], v[132:135], v[192:195], v[60:63]
	v_mfma_f32_16x16x32_bf16 v[56:59], v[140:143], v[192:195], v[56:59]
	v_mfma_f32_16x16x32_bf16 v[48:51], v[132:135], v[200:203], v[48:51]
	v_mfma_f32_16x16x32_bf16 v[40:43], v[140:143], v[200:203], v[40:43]
	v_mfma_f32_16x16x32_bf16 v[32:35], v[132:135], v[208:211], v[32:35]
	v_mfma_f32_16x16x32_bf16 v[24:27], v[140:143], v[208:211], v[24:27]
	v_mfma_f32_16x16x32_bf16 v[16:19], v[132:135], v[216:219], v[16:19]
	v_mfma_f32_16x16x32_bf16 v[8:11], v[140:143], v[216:219], v[8:11]
	v_mfma_f32_16x16x32_bf16 v[52:55], v[172:175], v[188:191], v[52:55]
	v_mfma_f32_16x16x32_bf16 v[44:47], v[180:183], v[188:191], v[44:47]
	v_mfma_f32_16x16x32_bf16 v[36:39], v[172:175], v[196:199], v[36:39]
	v_mfma_f32_16x16x32_bf16 v[28:31], v[180:183], v[196:199], v[28:31]
	v_mfma_f32_16x16x32_bf16 v[20:23], v[172:175], v[204:207], v[20:23]
	v_mfma_f32_16x16x32_bf16 v[12:15], v[180:183], v[204:207], v[12:15]
	v_mfma_f32_16x16x32_bf16 v[4:7], v[172:175], v[212:215], v[4:7]
	v_mfma_f32_16x16x32_bf16 v[0:3], v[180:183], v[212:215], v[0:3]
	v_mfma_f32_16x16x32_bf16 v[52:55], v[176:179], v[192:195], v[52:55]
	v_mfma_f32_16x16x32_bf16 v[44:47], v[184:187], v[192:195], v[44:47]
	v_mfma_f32_16x16x32_bf16 v[36:39], v[176:179], v[200:203], v[36:39]
	v_mfma_f32_16x16x32_bf16 v[28:31], v[184:187], v[200:203], v[28:31]
	v_mfma_f32_16x16x32_bf16 v[20:23], v[176:179], v[208:211], v[20:23]
	v_mfma_f32_16x16x32_bf16 v[12:15], v[184:187], v[208:211], v[12:15]
	v_mfma_f32_16x16x32_bf16 v[4:7], v[176:179], v[216:219], v[4:7]
	v_mfma_f32_16x16x32_bf16 v[0:3], v[184:187], v[216:219], v[0:3]
	s_setprio 0
	s_barrier
	s_add_i32 s82, 0, 0x18000
	s_add_i32 s83, 0, 0x1c000
	v_add_u32_e32 v140, s82, v166
	v_add_u32_e32 v152, s83, v166
	ds_read_b128 v[128:131], v140
	ds_read_b128 v[132:135], v140 offset:1024
	ds_read_b128 v[136:139], v140 offset:2048
	ds_read_b128 v[140:143], v140 offset:3072
	ds_read_b128 v[172:175], v152
	ds_read_b128 v[176:179], v152 offset:1024
	ds_read_b128 v[180:183], v152 offset:2048
	ds_read_b128 v[184:187], v152 offset:3072
	s_add_u32 s50, s50, 0x40000
	s_addc_u32 s51, s51, 0
	s_mov_b32 m0, s59
	v_lshl_add_u64 v[226:227], s[50:51], 0, v[150:151]
	ds_read_b128 v[188:191], v169 offset:32768
	ds_read_b128 v[192:195], v169 offset:33792
	ds_read_b128 v[196:199], v169 offset:34816
	ds_read_b128 v[200:203], v169 offset:35840
	ds_read_b128 v[204:207], v169 offset:36864
	ds_read_b128 v[208:211], v169 offset:37888
	ds_read_b128 v[212:215], v169 offset:38912
	ds_read_b128 v[216:219], v169 offset:39936
	global_load_lds_dwordx4 v[226:227], off
	s_mov_b32 m0, s60
	v_lshl_add_u64 v[226:227], s[50:51], 0, v[146:147]
	global_load_lds_dwordx4 v[226:227], off
	s_waitcnt vmcnt(8)
	s_waitcnt lgkmcnt(0)
	s_barrier
	s_setprio 1
	v_mfma_f32_16x16x32_bf16 v[124:127], v[128:131], v[188:191], v[124:127]
	v_mfma_f32_16x16x32_bf16 v[120:123], v[136:139], v[188:191], v[120:123]
	v_mfma_f32_16x16x32_bf16 v[116:119], v[128:131], v[196:199], v[116:119]
	v_mfma_f32_16x16x32_bf16 v[112:115], v[136:139], v[196:199], v[112:115]
	v_mfma_f32_16x16x32_bf16 v[108:111], v[128:131], v[204:207], v[108:111]
	v_mfma_f32_16x16x32_bf16 v[96:99], v[136:139], v[204:207], v[96:99]
	v_mfma_f32_16x16x32_bf16 v[80:83], v[128:131], v[212:215], v[80:83]
	v_mfma_f32_16x16x32_bf16 v[72:75], v[136:139], v[212:215], v[72:75]
	v_mfma_f32_16x16x32_bf16 v[124:127], v[132:135], v[192:195], v[124:127]
	v_mfma_f32_16x16x32_bf16 v[120:123], v[140:143], v[192:195], v[120:123]
	v_mfma_f32_16x16x32_bf16 v[116:119], v[132:135], v[200:203], v[116:119]
	v_mfma_f32_16x16x32_bf16 v[112:115], v[140:143], v[200:203], v[112:115]
	v_mfma_f32_16x16x32_bf16 v[108:111], v[132:135], v[208:211], v[108:111]
	v_mfma_f32_16x16x32_bf16 v[96:99], v[140:143], v[208:211], v[96:99]
	v_mfma_f32_16x16x32_bf16 v[80:83], v[132:135], v[216:219], v[80:83]
	v_mfma_f32_16x16x32_bf16 v[72:75], v[140:143], v[216:219], v[72:75]
	v_mfma_f32_16x16x32_bf16 v[104:107], v[172:175], v[188:191], v[104:107]
	v_mfma_f32_16x16x32_bf16 v[100:103], v[180:183], v[188:191], v[100:103]
	v_mfma_f32_16x16x32_bf16 v[92:95], v[172:175], v[196:199], v[92:95]
	v_mfma_f32_16x16x32_bf16 v[88:91], v[180:183], v[196:199], v[88:91]
	v_mfma_f32_16x16x32_bf16 v[84:87], v[172:175], v[204:207], v[84:87]
	v_mfma_f32_16x16x32_bf16 v[76:79], v[180:183], v[204:207], v[76:79]
	v_mfma_f32_16x16x32_bf16 v[68:71], v[172:175], v[212:215], v[68:71]
	v_mfma_f32_16x16x32_bf16 v[64:67], v[180:183], v[212:215], v[64:67]
	v_mfma_f32_16x16x32_bf16 v[104:107], v[176:179], v[192:195], v[104:107]
	v_mfma_f32_16x16x32_bf16 v[100:103], v[184:187], v[192:195], v[100:103]
	v_mfma_f32_16x16x32_bf16 v[92:95], v[176:179], v[200:203], v[92:95]
	v_mfma_f32_16x16x32_bf16 v[88:91], v[184:187], v[200:203], v[88:91]
	v_mfma_f32_16x16x32_bf16 v[84:87], v[176:179], v[208:211], v[84:87]
	v_mfma_f32_16x16x32_bf16 v[76:79], v[184:187], v[208:211], v[76:79]
	v_mfma_f32_16x16x32_bf16 v[68:71], v[176:179], v[216:219], v[68:71]
	v_mfma_f32_16x16x32_bf16 v[64:67], v[184:187], v[216:219], v[64:67]
	s_setprio 0
	s_barrier
; #define PG8_STAGE(bufoff, gbase, voff) do { _Pragma("unroll") for (int _i = 0; _i < 2; ++_i) \
;         __builtin_amdgcn_global_load_lds((const unsigned*)((const char*)(gbase) + (voff)[_i]), (LAS unsigned*)(lds + (bufoff) + ldsw + _i * 8192), 16, 0, 0); } while (0)
; #define PG8_LDA(dst, b, h) do { _Pragma("unroll") for (int m = 0; m < 4; ++m) _Pragma("unroll") for (int k = 0; k < 2; ++k) dst[m][k] = *(const LAS bf16x8*)(lds + PG8_SA(b, h) + aoff + m * 2048 + k * 1024); } while (0)
; #define PG8_MMA(ai, bj, At, Bt) do { __builtin_amdgcn_s_setprio(1); _Pragma("unroll") for (int m = 0; m < 4; ++m) _Pragma("unroll") for (int n = 0; n < 2; ++n) _Pragma("unroll") for (int k = 0; k < 2; ++k) \
;         acc[ai][bj][m][n] = __builtin_amdgcn_mfma_f32_16x16x32_bf16(Bt[n][k], At[m][k], acc[ai][bj][m][n], 0, 0, 0); __builtin_amdgcn_s_setprio(0); } while (0)
; #define PG8_WAIT_V(n) asm volatile("s_waitcnt vmcnt(" #n ")" ::: "memory")
; #define PG8_WAIT_L(n) asm volatile("s_waitcnt lgkmcnt(" #n ")" ::: "memory")
; #define PG8_BAR __builtin_amdgcn_s_barrier()
; #define PG8_SCHED __builtin_amdgcn_sched_barrier(0)
; template <class Epi, class Sched>
; __device__ __forceinline__ void gemm_phase(LAS unsigned char* lds, const Gemm g, const Sched& S, const Epi& E, const int wid) {
;     ...
;             PG8_LDA(At, 1, 1); PG8_STAGE(PG8_SB(1, 0), b3, voffB); PG8_STAGE(PG8_SB(1, 1), b3 + hstepB, voffB); PG8_STAGE(PG8_SA(1, 0), a3, voffA);
;             PG8_WAIT_V(8); PG8_WAIT_L(0); PG8_BAR; PG8_MMA(1, 0, At, B0); PG8_MMA(1, 1, At, B1); PG8_BAR; PG8_SCHED;
;         }
;         if (wr == 0) PG8_BAR;
	s_add_i32 s50, s82, s54
	v_lshl_add_u64 v[164:165], v[164:165], 0, s[16:17]
	s_mov_b32 m0, s50
	ds_read_b128 v[188:191], v169 offset:49152
	ds_read_b128 v[192:195], v169 offset:50176
	ds_read_b128 v[196:199], v169 offset:51200
	ds_read_b128 v[200:203], v169 offset:52224
	ds_read_b128 v[204:207], v169 offset:53248
	ds_read_b128 v[208:211], v169 offset:54272
	ds_read_b128 v[212:215], v169 offset:55296
	ds_read_b128 v[216:219], v169 offset:56320
	global_load_lds_dwordx4 v[164:165], off
	s_add_i32 m0, s50, 0x2000
	s_add_u32 s48, s48, 0x40080
	v_lshl_add_u64 v[164:165], v[220:221], 0, s[16:17]
	s_addc_u32 s49, s49, 0
	s_add_i32 s50, s83, s54
	global_load_lds_dwordx4 v[164:165], off
	s_mov_b32 m0, s50
	v_lshl_add_u64 v[164:165], s[48:49], 0, v[148:149]
	global_load_lds_dwordx4 v[164:165], off
	s_add_i32 m0, s50, 0x2000
	v_lshl_add_u64 v[164:165], s[48:49], 0, v[144:145]
	global_load_lds_dwordx4 v[164:165], off
	s_mov_b32 m0, s66
	v_lshl_add_u64 v[164:165], v[222:223], 0, s[16:17]
	global_load_lds_dwordx4 v[164:165], off
	s_mov_b32 m0, s67
	v_lshl_add_u64 v[164:165], v[224:225], 0, s[16:17]
	global_load_lds_dwordx4 v[164:165], off
	s_waitcnt vmcnt(8)
	s_waitcnt lgkmcnt(0)
	s_barrier
	s_setprio 1
	v_mfma_f32_16x16x32_bf16 v[60:63], v[128:131], v[188:191], v[60:63]
	v_mfma_f32_16x16x32_bf16 v[56:59], v[136:139], v[188:191], v[56:59]
	v_mfma_f32_16x16x32_bf16 v[48:51], v[128:131], v[196:199], v[48:51]
	v_mfma_f32_16x16x32_bf16 v[40:43], v[136:139], v[196:199], v[40:43]
	v_mfma_f32_16x16x32_bf16 v[32:35], v[128:131], v[204:207], v[32:35]
	v_mfma_f32_16x16x32_bf16 v[24:27], v[136:139], v[204:207], v[24:27]
	v_mfma_f32_16x16x32_bf16 v[16:19], v[128:131], v[212:215], v[16:19]
	v_mfma_f32_16x16x32_bf16 v[8:11], v[136:139], v[212:215], v[8:11]
	v_mfma_f32_16x16x32_bf16 v[60:63], v[132:135], v[192:195], v[60:63]
	v_mfma_f32_16x16x32_bf16 v[56:59], v[140:143], v[192:195], v[56:59]
	v_mfma_f32_16x16x32_bf16 v[48:51], v[132:135], v[200:203], v[48:51]
	v_mfma_f32_16x16x32_bf16 v[40:43], v[140:143], v[200:203], v[40:43]
	v_mfma_f32_16x16x32_bf16 v[32:35], v[132:135], v[208:211], v[32:35]
	v_mfma_f32_16x16x32_bf16 v[24:27], v[140:143], v[208:211], v[24:27]
	v_mfma_f32_16x16x32_bf16 v[16:19], v[132:135], v[216:219], v[16:19]
	v_mfma_f32_16x16x32_bf16 v[8:11], v[140:143], v[216:219], v[8:11]
	v_mfma_f32_16x16x32_bf16 v[52:55], v[172:175], v[188:191], v[52:55]
	v_mfma_f32_16x16x32_bf16 v[44:47], v[180:183], v[188:191], v[44:47]
	v_mfma_f32_16x16x32_bf16 v[36:39], v[172:175], v[196:199], v[36:39]
	v_mfma_f32_16x16x32_bf16 v[28:31], v[180:183], v[196:199], v[28:31]
	v_mfma_f32_16x16x32_bf16 v[20:23], v[172:175], v[204:207], v[20:23]
	v_mfma_f32_16x16x32_bf16 v[12:15], v[180:183], v[204:207], v[12:15]
	v_mfma_f32_16x16x32_bf16 v[4:7], v[172:175], v[212:215], v[4:7]
	v_mfma_f32_16x16x32_bf16 v[0:3], v[180:183], v[212:215], v[0:3]
	v_mfma_f32_16x16x32_bf16 v[52:55], v[176:179], v[192:195], v[52:55]
	v_mfma_f32_16x16x32_bf16 v[44:47], v[184:187], v[192:195], v[44:47]
	v_mfma_f32_16x16x32_bf16 v[36:39], v[176:179], v[200:203], v[36:39]
	v_mfma_f32_16x16x32_bf16 v[28:31], v[184:187], v[200:203], v[28:31]
	v_mfma_f32_16x16x32_bf16 v[20:23], v[176:179], v[208:211], v[20:23]
	v_mfma_f32_16x16x32_bf16 v[12:15], v[184:187], v[208:211], v[12:15]
	v_mfma_f32_16x16x32_bf16 v[4:7], v[176:179], v[216:219], v[4:7]
	v_mfma_f32_16x16x32_bf16 v[0:3], v[184:187], v[216:219], v[0:3]
	s_setprio 0
	s_add_i32 s81, s81, 2
	s_add_u32 s46, s46, 0x100
	s_addc_u32 s47, s47, 0
	s_add_u32 s79, s79, 0x100
	s_addc_u32 s80, s80, 0
	s_cmp_gt_u32 s81, 13
	s_barrier
	s_cbranch_scc0 .LBB0_546
	s_and_b64 vcc, exec, s[18:19]
	s_cbranch_vccz .LBB0_549
	s_barrier

; #define PG8_STAGE(bufoff, gbase, voff) do { _Pragma("unroll") for (int _i = 0; _i < 2; ++_i) \
;         __builtin_amdgcn_global_load_lds((const unsigned*)((const char*)(gbase) + (voff)[_i]), (LAS unsigned*)(lds + (bufoff) + ldsw + _i * 8192), 16, 0, 0); } while (0)
; #define PG8_LDA(dst, b, h) do { _Pragma("unroll") for (int m = 0; m < 4; ++m) _Pragma("unroll") for (int k = 0; k < 2; ++k) dst[m][k] = *(const LAS bf16x8*)(lds + PG8_SA(b, h) + aoff + m * 2048 + k * 1024); } while (0)
; #define PG8_LDB(dst, b, h) do { _Pragma("unroll") for (int n = 0; n < 2; ++n) _Pragma("unroll") for (int k = 0; k < 2; ++k) dst[n][k] = *(const LAS bf16x8*)(lds + PG8_SB(b, h) + boff + n * 2048 + k * 1024); } while (0)
; #define PG8_MMA(ai, bj, At, Bt) do { __builtin_amdgcn_s_setprio(1); _Pragma("unroll") for (int m = 0; m < 4; ++m) _Pragma("unroll") for (int n = 0; n < 2; ++n) _Pragma("unroll") for (int k = 0; k < 2; ++k) \
;         acc[ai][bj][m][n] = __builtin_amdgcn_mfma_f32_16x16x32_bf16(Bt[n][k], At[m][k], acc[ai][bj][m][n], 0, 0, 0); __builtin_amdgcn_s_setprio(0); } while (0)
; #define PG8_WAIT_V(n) asm volatile("s_waitcnt vmcnt(" #n ")" ::: "memory")
; #define PG8_WAIT_L(n) asm volatile("s_waitcnt lgkmcnt(" #n ")" ::: "memory")
; #define PG8_BAR __builtin_amdgcn_s_barrier()
; #define PG8_SCHED __builtin_amdgcn_sched_barrier(0)
; template <class Epi, class Sched>
; __device__ __forceinline__ void gemm_phase(LAS unsigned char* lds, const Gemm g, const Sched& S, const Epi& E, const int wid) {
;     ...
;             const bool last = (t == nt - 2);
;             const char* a1 = cA + (size_t)(t + 1) * kstep;
;             const char* a2 = last ? nA : cA + (size_t)(t + 2) * kstep; const char* b2 = last ? nB : cB + (size_t)(t + 2) * kstep;
;             const char* a3 = a2 + kstep; const char* b3 = b2 + kstep;
;             PG8_LDB(B0, 0, 0); PG8_LDB(B1, 0, 1); PG8_SCHED; PG8_LDA(At, 0, 0); PG8_STAGE(PG8_SA(1, 1), a1 + hstepA, voffA);
;             PG8_WAIT_V(8); PG8_WAIT_L(0); PG8_BAR; PG8_MMA(0, 0, At, B0); PG8_MMA(0, 1, At, B1); PG8_BAR; PG8_SCHED;
;             PG8_LDA(At, 0, 1); PG8_STAGE(PG8_SB(0, 0), b2, voffB); PG8_STAGE(PG8_SB(0, 1), b2 + hstepB, voffB); PG8_STAGE(PG8_SA(0, 0), a2, voffA);
;             PG8_WAIT_V(8); PG8_WAIT_L(0); PG8_BAR; PG8_MMA(1, 0, At, B0); PG8_MMA(1, 1, At, B1); PG8_BAR; PG8_SCHED;
.LBB0_680:
	ds_read_b128 v[128:131], v235
	ds_read_b128 v[132:135], v235 offset:1024
	ds_read_b128 v[136:139], v235 offset:2048
	ds_read_b128 v[140:143], v235 offset:3072
	ds_read_b128 v[144:147], v236
	ds_read_b128 v[148:151], v236 offset:1024
	ds_read_b128 v[152:155], v236 offset:2048
	ds_read_b128 v[156:159], v236 offset:3072
	s_add_u32 s34, s30, 0xfffc0080
	s_addc_u32 s35, s31, -1
	s_cmp_eq_u32 s63, 12
	s_cselect_b32 s37, s21, s35
	s_cselect_b32 s36, s59, s34
	s_cselect_b32 s35, s19, s62
	s_cselect_b32 s34, s60, s61
	v_lshl_add_u64 v[192:193], s[30:31], 0, v[214:215]
	s_add_i32 m0, s44, 0xc000
	ds_read_b128 v[160:163], v237
	ds_read_b128 v[164:167], v237 offset:1024
	ds_read_b128 v[168:171], v237 offset:2048
	ds_read_b128 v[172:175], v237 offset:3072
	ds_read_b128 v[176:179], v237 offset:4096
	ds_read_b128 v[180:183], v237 offset:5120
	ds_read_b128 v[184:187], v237 offset:6144
	ds_read_b128 v[188:191], v237 offset:7168
	global_load_lds_dwordx4 v[192:193], off
	s_add_i32 m0, s44, 0xe000
	v_lshl_add_u64 v[192:193], s[30:31], 0, v[216:217]
	global_load_lds_dwordx4 v[192:193], off
	s_waitcnt vmcnt(8)
	s_waitcnt lgkmcnt(0)
	s_barrier
	s_setprio 1
	v_mfma_f32_16x16x32_bf16 v[124:127], v[128:131], v[160:163], v[124:127]
	v_mfma_f32_16x16x32_bf16 v[120:123], v[136:139], v[160:163], v[120:123]
	v_mfma_f32_16x16x32_bf16 v[112:115], v[128:131], v[168:171], v[112:115]
	v_mfma_f32_16x16x32_bf16 v[104:107], v[136:139], v[168:171], v[104:107]
	v_mfma_f32_16x16x32_bf16 v[96:99], v[128:131], v[176:179], v[96:99]
	v_mfma_f32_16x16x32_bf16 v[88:91], v[136:139], v[176:179], v[88:91]
	v_mfma_f32_16x16x32_bf16 v[76:79], v[128:131], v[184:187], v[76:79]
	v_mfma_f32_16x16x32_bf16 v[72:75], v[136:139], v[184:187], v[72:75]
	v_mfma_f32_16x16x32_bf16 v[124:127], v[132:135], v[164:167], v[124:127]
	v_mfma_f32_16x16x32_bf16 v[120:123], v[140:143], v[164:167], v[120:123]
	v_mfma_f32_16x16x32_bf16 v[112:115], v[132:135], v[172:175], v[112:115]
	v_mfma_f32_16x16x32_bf16 v[104:107], v[140:143], v[172:175], v[104:107]
	v_mfma_f32_16x16x32_bf16 v[96:99], v[132:135], v[180:183], v[96:99]
	v_mfma_f32_16x16x32_bf16 v[88:91], v[140:143], v[180:183], v[88:91]
	v_mfma_f32_16x16x32_bf16 v[76:79], v[132:135], v[188:191], v[76:79]
	v_mfma_f32_16x16x32_bf16 v[72:75], v[140:143], v[188:191], v[72:75]
	v_mfma_f32_16x16x32_bf16 v[116:119], v[144:147], v[160:163], v[116:119]
	v_mfma_f32_16x16x32_bf16 v[108:111], v[152:155], v[160:163], v[108:111]
	v_mfma_f32_16x16x32_bf16 v[100:103], v[144:147], v[168:171], v[100:103]
	v_mfma_f32_16x16x32_bf16 v[92:95], v[152:155], v[168:171], v[92:95]
	v_mfma_f32_16x16x32_bf16 v[84:87], v[144:147], v[176:179], v[84:87]
	v_mfma_f32_16x16x32_bf16 v[80:83], v[152:155], v[176:179], v[80:83]
	v_mfma_f32_16x16x32_bf16 v[68:71], v[144:147], v[184:187], v[68:71]
	v_mfma_f32_16x16x32_bf16 v[64:67], v[152:155], v[184:187], v[64:67]
	v_mfma_f32_16x16x32_bf16 v[116:119], v[148:151], v[164:167], v[116:119]
	v_mfma_f32_16x16x32_bf16 v[108:111], v[156:159], v[164:167], v[108:111]
	v_mfma_f32_16x16x32_bf16 v[100:103], v[148:151], v[172:175], v[100:103]
	v_mfma_f32_16x16x32_bf16 v[92:95], v[156:159], v[172:175], v[92:95]
	v_mfma_f32_16x16x32_bf16 v[84:87], v[148:151], v[180:183], v[84:87]
	v_mfma_f32_16x16x32_bf16 v[80:83], v[156:159], v[180:183], v[80:83]
	v_mfma_f32_16x16x32_bf16 v[68:71], v[148:151], v[188:191], v[68:71]
	v_mfma_f32_16x16x32_bf16 v[64:67], v[156:159], v[188:191], v[64:67]
	s_setprio 0
	s_barrier
	s_add_i32 s64, s51, s41
	v_lshl_add_u64 v[192:193], s[34:35], 0, v[210:211]
	s_mov_b32 m0, s64
	ds_read_b128 v[160:163], v237 offset:16384
	ds_read_b128 v[164:167], v237 offset:17408
	ds_read_b128 v[168:171], v237 offset:18432
	ds_read_b128 v[172:175], v237 offset:19456
	ds_read_b128 v[176:179], v237 offset:20480
	ds_read_b128 v[180:183], v237 offset:21504
	ds_read_b128 v[184:187], v237 offset:22528
	ds_read_b128 v[188:191], v237 offset:23552
	global_load_lds_dwordx4 v[192:193], off
	s_add_i32 m0, s64, 0x2000
	s_add_u32 s64, s34, 0x40000
	v_lshl_add_u64 v[194:195], s[34:35], 0, v[208:209]
	s_addc_u32 s65, s35, 0
	s_add_i32 s66, s52, s41
	global_load_lds_dwordx4 v[194:195], off
	v_lshl_add_u64 v[196:197], s[64:65], 0, v[210:211]
	s_mov_b32 m0, s66
	v_lshl_add_u64 v[198:199], s[36:37], 0, v[208:209]
	global_load_lds_dwordx4 v[196:197], off
	s_add_i32 m0, s66, 0x2000
	v_lshl_add_u64 v[196:197], s[64:65], 0, v[208:209]
	global_load_lds_dwordx4 v[196:197], off
	s_mov_b32 m0, s44
	v_lshl_add_u64 v[196:197], s[36:37], 0, v[210:211]
	global_load_lds_dwordx4 v[196:197], off
	s_mov_b32 m0, s45
	s_nop 0
	global_load_lds_dwordx4 v[198:199], off
	s_waitcnt vmcnt(8)
	s_waitcnt lgkmcnt(0)
	s_barrier
; #define PG8_STAGE(bufoff, gbase, voff) do { _Pragma("unroll") for (int _i = 0; _i < 2; ++_i) \
;         __builtin_amdgcn_global_load_lds((const unsigned*)((const char*)(gbase) + (voff)[_i]), (LAS unsigned*)(lds + (bufoff) + ldsw + _i * 8192), 16, 0, 0); } while (0)
; #define PG8_LDA(dst, b, h) do { _Pragma("unroll") for (int m = 0; m < 4; ++m) _Pragma("unroll") for (int k = 0; k < 2; ++k) dst[m][k] = *(const LAS bf16x8*)(lds + PG8_SA(b, h) + aoff + m * 2048 + k * 1024); } while (0)
; #define PG8_LDB(dst, b, h) do { _Pragma("unroll") for (int n = 0; n < 2; ++n) _Pragma("unroll") for (int k = 0; k < 2; ++k) dst[n][k] = *(const LAS bf16x8*)(lds + PG8_SB(b, h) + boff + n * 2048 + k * 1024); } while (0)
; #define PG8_MMA(ai, bj, At, Bt) do { __builtin_amdgcn_s_setprio(1); _Pragma("unroll") for (int m = 0; m < 4; ++m) _Pragma("unroll") for (int n = 0; n < 2; ++n) _Pragma("unroll") for (int k = 0; k < 2; ++k) \
;         acc[ai][bj][m][n] = __builtin_amdgcn_mfma_f32_16x16x32_bf16(Bt[n][k], At[m][k], acc[ai][bj][m][n], 0, 0, 0); __builtin_amdgcn_s_setprio(0); } while (0)
; #define PG8_WAIT_V(n) asm volatile("s_waitcnt vmcnt(" #n ")" ::: "memory")
; #define PG8_WAIT_L(n) asm volatile("s_waitcnt lgkmcnt(" #n ")" ::: "memory")
; #define PG8_BAR __builtin_amdgcn_s_barrier()
; #define PG8_SCHED __builtin_amdgcn_sched_barrier(0)
; template <class Epi, class Sched>
; __device__ __forceinline__ void gemm_phase(LAS unsigned char* lds, const Gemm g, const Sched& S, const Epi& E, const int wid) {
;     ...
;             PG8_WAIT_V(8); PG8_WAIT_L(0); PG8_BAR; PG8_MMA(1, 0, At, B0); PG8_MMA(1, 1, At, B1); PG8_BAR; PG8_SCHED;
;             PG8_LDB(B0, 1, 0); PG8_LDB(B1, 1, 1); PG8_SCHED; PG8_LDA(At, 1, 0); PG8_STAGE(PG8_SA(0, 1), a2 + hstepA, voffA);
;             PG8_WAIT_V(8); PG8_WAIT_L(0); PG8_BAR; PG8_MMA(0, 0, At, B0); PG8_MMA(0, 1, At, B1); PG8_BAR; PG8_SCHED;
	s_setprio 1
	v_mfma_f32_16x16x32_bf16 v[60:63], v[128:131], v[160:163], v[60:63]
	v_mfma_f32_16x16x32_bf16 v[56:59], v[136:139], v[160:163], v[56:59]
	v_mfma_f32_16x16x32_bf16 v[48:51], v[128:131], v[168:171], v[48:51]
	v_mfma_f32_16x16x32_bf16 v[40:43], v[136:139], v[168:171], v[40:43]
	v_mfma_f32_16x16x32_bf16 v[32:35], v[128:131], v[176:179], v[32:35]
	v_mfma_f32_16x16x32_bf16 v[24:27], v[136:139], v[176:179], v[24:27]
	v_mfma_f32_16x16x32_bf16 v[12:15], v[128:131], v[184:187], v[12:15]
	v_mfma_f32_16x16x32_bf16 v[8:11], v[136:139], v[184:187], v[8:11]
	v_mfma_f32_16x16x32_bf16 v[60:63], v[132:135], v[164:167], v[60:63]
	v_mfma_f32_16x16x32_bf16 v[56:59], v[140:143], v[164:167], v[56:59]
	v_mfma_f32_16x16x32_bf16 v[48:51], v[132:135], v[172:175], v[48:51]
	v_mfma_f32_16x16x32_bf16 v[40:43], v[140:143], v[172:175], v[40:43]
	v_mfma_f32_16x16x32_bf16 v[32:35], v[132:135], v[180:183], v[32:35]
	v_mfma_f32_16x16x32_bf16 v[24:27], v[140:143], v[180:183], v[24:27]
	v_mfma_f32_16x16x32_bf16 v[12:15], v[132:135], v[188:191], v[12:15]
	v_mfma_f32_16x16x32_bf16 v[8:11], v[140:143], v[188:191], v[8:11]
	v_mfma_f32_16x16x32_bf16 v[52:55], v[144:147], v[160:163], v[52:55]
	v_mfma_f32_16x16x32_bf16 v[44:47], v[152:155], v[160:163], v[44:47]
	v_mfma_f32_16x16x32_bf16 v[36:39], v[144:147], v[168:171], v[36:39]
	v_mfma_f32_16x16x32_bf16 v[28:31], v[152:155], v[168:171], v[28:31]
	v_mfma_f32_16x16x32_bf16 v[20:23], v[144:147], v[176:179], v[20:23]
	v_mfma_f32_16x16x32_bf16 v[16:19], v[152:155], v[176:179], v[16:19]
	v_mfma_f32_16x16x32_bf16 v[4:7], v[144:147], v[184:187], v[4:7]
	v_mfma_f32_16x16x32_bf16 v[0:3], v[152:155], v[184:187], v[0:3]
	v_mfma_f32_16x16x32_bf16 v[52:55], v[148:151], v[164:167], v[52:55]
	v_mfma_f32_16x16x32_bf16 v[44:47], v[156:159], v[164:167], v[44:47]
	v_mfma_f32_16x16x32_bf16 v[36:39], v[148:151], v[172:175], v[36:39]
	v_mfma_f32_16x16x32_bf16 v[28:31], v[156:159], v[172:175], v[28:31]
	v_mfma_f32_16x16x32_bf16 v[20:23], v[148:151], v[180:183], v[20:23]
	v_mfma_f32_16x16x32_bf16 v[16:19], v[156:159], v[180:183], v[16:19]
	v_mfma_f32_16x16x32_bf16 v[4:7], v[148:151], v[188:191], v[4:7]
	v_mfma_f32_16x16x32_bf16 v[0:3], v[156:159], v[188:191], v[0:3]
	s_setprio 0
	s_barrier
	s_add_i32 s64, 0, 0x18000
	s_add_i32 s65, 0, 0x1c000
	v_add_u32_e32 v140, s64, v233
	v_add_u32_e32 v156, s65, v233
	ds_read_b128 v[128:131], v140
	ds_read_b128 v[132:135], v140 offset:1024
	ds_read_b128 v[136:139], v140 offset:2048
	ds_read_b128 v[140:143], v140 offset:3072
	ds_read_b128 v[144:147], v156
	ds_read_b128 v[148:151], v156 offset:1024
	ds_read_b128 v[152:155], v156 offset:2048
	ds_read_b128 v[156:159], v156 offset:3072
	s_add_u32 s36, s36, 0x40000
	s_addc_u32 s37, s37, 0
	s_mov_b32 m0, s46
	v_lshl_add_u64 v[200:201], s[36:37], 0, v[210:211]
	ds_read_b128 v[160:163], v237 offset:32768
	ds_read_b128 v[164:167], v237 offset:33792
	ds_read_b128 v[168:171], v237 offset:34816
	ds_read_b128 v[172:175], v237 offset:35840
	ds_read_b128 v[176:179], v237 offset:36864
	ds_read_b128 v[180:183], v237 offset:37888
	ds_read_b128 v[184:187], v237 offset:38912
	ds_read_b128 v[188:191], v237 offset:39936
	global_load_lds_dwordx4 v[200:201], off
	s_mov_b32 m0, s47
	v_lshl_add_u64 v[200:201], s[36:37], 0, v[208:209]
	global_load_lds_dwordx4 v[200:201], off
	s_waitcnt vmcnt(8)
	s_waitcnt lgkmcnt(0)
	s_barrier
	s_setprio 1
	v_mfma_f32_16x16x32_bf16 v[124:127], v[128:131], v[160:163], v[124:127]
	v_mfma_f32_16x16x32_bf16 v[120:123], v[136:139], v[160:163], v[120:123]
	v_mfma_f32_16x16x32_bf16 v[112:115], v[128:131], v[168:171], v[112:115]
	v_mfma_f32_16x16x32_bf16 v[104:107], v[136:139], v[168:171], v[104:107]
	v_mfma_f32_16x16x32_bf16 v[96:99], v[128:131], v[176:179], v[96:99]
	v_mfma_f32_16x16x32_bf16 v[88:91], v[136:139], v[176:179], v[88:91]
	v_mfma_f32_16x16x32_bf16 v[76:79], v[128:131], v[184:187], v[76:79]
	v_mfma_f32_16x16x32_bf16 v[72:75], v[136:139], v[184:187], v[72:75]
	v_mfma_f32_16x16x32_bf16 v[124:127], v[132:135], v[164:167], v[124:127]
	v_mfma_f32_16x16x32_bf16 v[120:123], v[140:143], v[164:167], v[120:123]
	v_mfma_f32_16x16x32_bf16 v[112:115], v[132:135], v[172:175], v[112:115]
	v_mfma_f32_16x16x32_bf16 v[104:107], v[140:143], v[172:175], v[104:107]
	v_mfma_f32_16x16x32_bf16 v[96:99], v[132:135], v[180:183], v[96:99]
	v_mfma_f32_16x16x32_bf16 v[88:91], v[140:143], v[180:183], v[88:91]
	v_mfma_f32_16x16x32_bf16 v[76:79], v[132:135], v[188:191], v[76:79]
	v_mfma_f32_16x16x32_bf16 v[72:75], v[140:143], v[188:191], v[72:75]
	v_mfma_f32_16x16x32_bf16 v[116:119], v[144:147], v[160:163], v[116:119]
	v_mfma_f32_16x16x32_bf16 v[108:111], v[152:155], v[160:163], v[108:111]
	v_mfma_f32_16x16x32_bf16 v[100:103], v[144:147], v[168:171], v[100:103]
	v_mfma_f32_16x16x32_bf16 v[92:95], v[152:155], v[168:171], v[92:95]
	v_mfma_f32_16x16x32_bf16 v[84:87], v[144:147], v[176:179], v[84:87]
	v_mfma_f32_16x16x32_bf16 v[80:83], v[152:155], v[176:179], v[80:83]
	v_mfma_f32_16x16x32_bf16 v[68:71], v[144:147], v[184:187], v[68:71]
	v_mfma_f32_16x16x32_bf16 v[64:67], v[152:155], v[184:187], v[64:67]
	v_mfma_f32_16x16x32_bf16 v[116:119], v[148:151], v[164:167], v[116:119]
	v_mfma_f32_16x16x32_bf16 v[108:111], v[156:159], v[164:167], v[108:111]
	v_mfma_f32_16x16x32_bf16 v[100:103], v[148:151], v[172:175], v[100:103]
	v_mfma_f32_16x16x32_bf16 v[92:95], v[156:159], v[172:175], v[92:95]
	v_mfma_f32_16x16x32_bf16 v[84:87], v[148:151], v[180:183], v[84:87]
	v_mfma_f32_16x16x32_bf16 v[80:83], v[156:159], v[180:183], v[80:83]
	v_mfma_f32_16x16x32_bf16 v[68:71], v[148:151], v[188:191], v[68:71]
	v_mfma_f32_16x16x32_bf16 v[64:67], v[156:159], v[188:191], v[64:67]
	s_setprio 0
	s_barrier
; #define PG8_STAGE(bufoff, gbase, voff) do { _Pragma("unroll") for (int _i = 0; _i < 2; ++_i) \
;         __builtin_amdgcn_global_load_lds((const unsigned*)((const char*)(gbase) + (voff)[_i]), (LAS unsigned*)(lds + (bufoff) + ldsw + _i * 8192), 16, 0, 0); } while (0)
; #define PG8_LDA(dst, b, h) do { _Pragma("unroll") for (int m = 0; m < 4; ++m) _Pragma("unroll") for (int k = 0; k < 2; ++k) dst[m][k] = *(const LAS bf16x8*)(lds + PG8_SA(b, h) + aoff + m * 2048 + k * 1024); } while (0)
; #define PG8_MMA(ai, bj, At, Bt) do { __builtin_amdgcn_s_setprio(1); _Pragma("unroll") for (int m = 0; m < 4; ++m) _Pragma("unroll") for (int n = 0; n < 2; ++n) _Pragma("unroll") for (int k = 0; k < 2; ++k) \
;         acc[ai][bj][m][n] = __builtin_amdgcn_mfma_f32_16x16x32_bf16(Bt[n][k], At[m][k], acc[ai][bj][m][n], 0, 0, 0); __builtin_amdgcn_s_setprio(0); } while (0)
; #define PG8_WAIT_V(n) asm volatile("s_waitcnt vmcnt(" #n ")" ::: "memory")
; #define PG8_WAIT_L(n) asm volatile("s_waitcnt lgkmcnt(" #n ")" ::: "memory")
; #define PG8_BAR __builtin_amdgcn_s_barrier()
; #define PG8_SCHED __builtin_amdgcn_sched_barrier(0)
; template <class Epi, class Sched>
; __device__ __forceinline__ void gemm_phase(LAS unsigned char* lds, const Gemm g, const Sched& S, const Epi& E, const int wid) {
;     ...
;             PG8_LDA(At, 1, 1); PG8_STAGE(PG8_SB(1, 0), b3, voffB); PG8_STAGE(PG8_SB(1, 1), b3 + hstepB, voffB); PG8_STAGE(PG8_SA(1, 0), a3, voffA);
;             PG8_WAIT_V(8); PG8_WAIT_L(0); PG8_BAR; PG8_MMA(1, 0, At, B0); PG8_MMA(1, 1, At, B1); PG8_BAR; PG8_SCHED;
;         }
;         if (wr == 0) PG8_BAR;
	s_add_i32 s36, s64, s41
	v_lshl_add_u64 v[192:193], v[192:193], 0, s[12:13]
	s_mov_b32 m0, s36
	ds_read_b128 v[160:163], v237 offset:49152
	ds_read_b128 v[164:167], v237 offset:50176
	ds_read_b128 v[168:171], v237 offset:51200
	ds_read_b128 v[172:175], v237 offset:52224
	ds_read_b128 v[176:179], v237 offset:53248
	ds_read_b128 v[180:183], v237 offset:54272
	ds_read_b128 v[184:187], v237 offset:55296
	ds_read_b128 v[188:191], v237 offset:56320
	global_load_lds_dwordx4 v[192:193], off
	s_add_i32 m0, s36, 0x2000
	s_add_u32 s34, s34, 0x40080
	v_lshl_add_u64 v[192:193], v[194:195], 0, s[12:13]
	s_addc_u32 s35, s35, 0
	s_add_i32 s36, s65, s41
	global_load_lds_dwordx4 v[192:193], off
	s_mov_b32 m0, s36
	v_lshl_add_u64 v[192:193], s[34:35], 0, v[210:211]
	global_load_lds_dwordx4 v[192:193], off
	s_add_i32 m0, s36, 0x2000
	v_lshl_add_u64 v[192:193], s[34:35], 0, v[208:209]
	global_load_lds_dwordx4 v[192:193], off
	s_mov_b32 m0, s33
	v_lshl_add_u64 v[192:193], v[196:197], 0, s[12:13]
	global_load_lds_dwordx4 v[192:193], off
	s_mov_b32 m0, s50
	v_lshl_add_u64 v[192:193], v[198:199], 0, s[12:13]
	global_load_lds_dwordx4 v[192:193], off
	s_waitcnt vmcnt(8)
	s_waitcnt lgkmcnt(0)
	s_barrier
	s_setprio 1
	v_mfma_f32_16x16x32_bf16 v[60:63], v[128:131], v[160:163], v[60:63]
	v_mfma_f32_16x16x32_bf16 v[56:59], v[136:139], v[160:163], v[56:59]
	v_mfma_f32_16x16x32_bf16 v[48:51], v[128:131], v[168:171], v[48:51]
	v_mfma_f32_16x16x32_bf16 v[40:43], v[136:139], v[168:171], v[40:43]
	v_mfma_f32_16x16x32_bf16 v[32:35], v[128:131], v[176:179], v[32:35]
	v_mfma_f32_16x16x32_bf16 v[24:27], v[136:139], v[176:179], v[24:27]
	v_mfma_f32_16x16x32_bf16 v[12:15], v[128:131], v[184:187], v[12:15]
	v_mfma_f32_16x16x32_bf16 v[8:11], v[136:139], v[184:187], v[8:11]
	v_mfma_f32_16x16x32_bf16 v[60:63], v[132:135], v[164:167], v[60:63]
	v_mfma_f32_16x16x32_bf16 v[56:59], v[140:143], v[164:167], v[56:59]
	v_mfma_f32_16x16x32_bf16 v[48:51], v[132:135], v[172:175], v[48:51]
	v_mfma_f32_16x16x32_bf16 v[40:43], v[140:143], v[172:175], v[40:43]
	v_mfma_f32_16x16x32_bf16 v[32:35], v[132:135], v[180:183], v[32:35]
	v_mfma_f32_16x16x32_bf16 v[24:27], v[140:143], v[180:183], v[24:27]
	v_mfma_f32_16x16x32_bf16 v[12:15], v[132:135], v[188:191], v[12:15]
	v_mfma_f32_16x16x32_bf16 v[8:11], v[140:143], v[188:191], v[8:11]
	v_mfma_f32_16x16x32_bf16 v[52:55], v[144:147], v[160:163], v[52:55]
	v_mfma_f32_16x16x32_bf16 v[44:47], v[152:155], v[160:163], v[44:47]
	v_mfma_f32_16x16x32_bf16 v[36:39], v[144:147], v[168:171], v[36:39]
	v_mfma_f32_16x16x32_bf16 v[28:31], v[152:155], v[168:171], v[28:31]
	v_mfma_f32_16x16x32_bf16 v[20:23], v[144:147], v[176:179], v[20:23]
	v_mfma_f32_16x16x32_bf16 v[16:19], v[152:155], v[176:179], v[16:19]
	v_mfma_f32_16x16x32_bf16 v[4:7], v[144:147], v[184:187], v[4:7]
	v_mfma_f32_16x16x32_bf16 v[0:3], v[152:155], v[184:187], v[0:3]
	v_mfma_f32_16x16x32_bf16 v[52:55], v[148:151], v[164:167], v[52:55]
	v_mfma_f32_16x16x32_bf16 v[44:47], v[156:159], v[164:167], v[44:47]
	v_mfma_f32_16x16x32_bf16 v[36:39], v[148:151], v[172:175], v[36:39]
	v_mfma_f32_16x16x32_bf16 v[28:31], v[156:159], v[172:175], v[28:31]
	v_mfma_f32_16x16x32_bf16 v[20:23], v[148:151], v[180:183], v[20:23]
	v_mfma_f32_16x16x32_bf16 v[16:19], v[156:159], v[180:183], v[16:19]
	v_mfma_f32_16x16x32_bf16 v[4:7], v[148:151], v[188:191], v[4:7]
	v_mfma_f32_16x16x32_bf16 v[0:3], v[156:159], v[188:191], v[0:3]
	s_setprio 0
	s_add_i32 s63, s63, 2
	s_add_u32 s30, s30, 0x100
	s_addc_u32 s31, s31, 0
	s_add_u32 s61, s61, 0x100
	s_addc_u32 s62, s62, 0
	s_cmp_gt_u32 s63, 13
	s_barrier
	s_cbranch_scc0 .LBB0_680
	s_and_b64 vcc, exec, s[14:15]
	s_cbranch_vccz .LBB0_683
	s_barrier
